# peer_q k-loop: each wave stages only its own 32 token rows (wave-private LDS rows), one workgroup barrier per k-step instead of two
# speedup vs baseline: 1.0496x; 1.0043x over previous
;   DI u16* hb() const { return (u16*)(ws + OFF_hb); }
; #define tid_opaque() tid_from(WAVE_S)
;   const int tid = tid_opaque(), lane = tid & 63;
;   u16* Xs = lds;
;   u16* Ys = lds + 128 * LSTR;
;   const int lr = tid >> 3, lc = (tid & 7) * 8;
;   const u16* xg = X + (size_t)lr * RS + lc;
;   const u16* yg = Y + (size_t)lr * RS + lc;
;   u32x4 xr[4], yr[4];
; #pragma unroll
;   for (int it = 0; it < 4; ++it) {
;     xr[it] = *(const u32x4*)(xg + (size_t)it * 32 * RS);
;     yr[it] = *(const u32x4*)(yg + (size_t)it * 32 * RS);
;   }
; DI void phase_peer_q(const Params& p, int layer, u16* lds, const int WAVE_S) {
;     ...
;       gemm_tile<4, 1>(W + (size_t)(head * 2 + half) * 128 * DM, p.hb() + (size_t)tt * 128 * DM, acc, lds, 0, wave * 32, WAVE_S);
.LBB0_390:
	s_or_b32 s28, s19, s18
	v_mbcnt_lo_u32_b32 v12, -1, 0
	v_mbcnt_hi_u32_b32 v12, -1, v12
	s_xor_b64 s[46:47], s[48:49], -1
	v_add_u32_e32 v0, s33, v12
	s_lshl_b64 s[50:51], s[28:29], 1
	v_ashrrev_i32_e32 v2, 3, v0
	s_add_u32 s50, s84, s50
	v_ashrrev_i32_e32 v3, 31, v2
	s_addc_u32 s51, s85, s51
	v_lshlrev_b64 v[4:5], 11, v[2:3]
	v_lshlrev_b32_e32 v0, 4, v12
	v_lshl_add_u64 v[6:7], s[50:51], 0, v[4:5]
	v_and_b32_e32 v0, 0x70, v0
	s_mov_b32 s100, s50
	s_mov_b32 s101, s51
	s_lshr_b32 vcc_lo, s33, 7
	s_lshl_b32 vcc_lo, vcc_lo, 5
	s_lshr_b32 s32, s33, 6
	s_lshl_b32 s32, s32, 12
	s_add_u32 s41, s32, 0x8000
	s_add_u32 s41, s41, vcc_lo
	s_lshr_b32 vcc_lo, s33, 1
	v_lshrrev_b32_e32 v135, 3, v12
	v_add_u32_e32 v135, vcc_lo, v135
	v_lshlrev_b32_e32 v135, 11, v135
	v_and_b32_e32 v136, 7, v12
	v_lshrrev_b32_e32 v137, 4, v12
	v_xor_b32_e32 v136, v136, v137
	v_lshl_add_u32 v120, v136, 4, v135
	v_and_b32_e32 v134, 7, v12
	v_lshl_add_u32 v119, v134, 4, v135
	v_lshrrev_b32_e32 v134, 3, v12
	v_lshlrev_b32_e32 v134, 7, v134
	v_lshl_add_u32 v118, v136, 4, v134
	v_add_u32_e32 v118, s32, v118
	v_xor_b32_e32 v136, 4, v136
	v_lshl_add_u32 v121, v136, 4, v135
	v_add_u32_e32 v121, 0x3c00, v121
	v_and_b32_e32 v138, 31, v12
	v_lshlrev_b32_e32 v138, 7, v138
	v_bfe_u32 v139, v12, 1, 3
	v_lshrrev_b32_e32 v140, 5, v12
	v_xor_b32_e32 v139, v139, v140
	v_xor_b32_e32 v141, 0, v139
	v_lshl_add_u32 v114, v141, 4, v138
	v_xor_b32_e32 v141, 2, v139
	v_lshl_add_u32 v115, v141, 4, v138
	v_xor_b32_e32 v141, 4, v139
	v_lshl_add_u32 v116, v141, 4, v138
	v_xor_b32_e32 v141, 6, v139
	v_lshl_add_u32 v117, v141, 4, v138
	v_lshl_add_u64 v[6:7], v[6:7], 0, v[0:1]
	v_lshl_add_u64 v[8:9], s[44:45], 0, v[4:5]
	s_nop 0
	v_add_co_u32_e32 v8, vcc, s81, v6
	global_load_dwordx4 v[70:73], v119, s[44:45]
	v_add_u32_e32 v133, 0x4000, v119
	global_load_dwordx4 v[78:81], v133, s[44:45]
	v_addc_co_u32_e32 v9, vcc, 0, v7, vcc
	v_add_co_u32_e32 v10, vcc, s81, v116
	v_and_b32_e32 v3, 31, v12
	s_nop 0
	v_addc_co_u32_e32 v11, vcc, 0, v117, vcc
	v_add_u32_e32 v133, 0x8000, v119
	global_load_dwordx4 v[86:89], v133, s[44:45]
	v_add_u32_e32 v133, 0xc000, v119
	global_load_dwordx4 v[94:97], v133, s[44:45]
	v_add_co_u32_e32 v8, vcc, s12, v6
	s_nop 0
	s_nop 0
	v_addc_co_u32_e32 v9, vcc, 0, v7, vcc
	v_add_co_u32_e32 v10, vcc, s12, v116
	s_add_i32 s28, s18, s19
	s_nop 0
	v_addc_co_u32_e32 v11, vcc, 0, v117, vcc
	v_add_co_u32_e32 v6, vcc, s86, v6
	s_mov_b32 m0, s32
	s_nop 0
	global_load_lds_dwordx4 v120, s[100:101]
	global_load_lds_dwordx4 v121, s[100:101] offset:1024
	v_add_u32_e32 v133, 0x7800, v120
	global_load_lds_dwordx4 v133, s[100:101] offset:2048
	v_add_u32_e32 v133, 0x7800, v121
	global_load_lds_dwordx4 v133, s[100:101] offset:3072
	v_addc_co_u32_e32 v7, vcc, 0, v7, vcc
	v_add_co_u32_e32 v8, vcc, s86, v116
	v_and_b32_e32 v0, 7, v12
	s_nop 0
	v_addc_co_u32_e32 v9, vcc, 0, v117, vcc
	global_load_dwordx4 v[66:69], v119, s[44:45] offset:128
	v_add_u32_e32 v133, 0x4000, v119
	global_load_dwordx4 v[74:77], v133, s[44:45] offset:128
	v_add_u32_e32 v133, 0x8000, v119
	global_load_dwordx4 v[82:85], v133, s[44:45] offset:128
	v_add_u32_e32 v133, 0xc000, v119
	global_load_dwordx4 v[90:93], v133, s[44:45] offset:128
	v_lshrrev_b32_e32 v6, 1, v12
	v_and_b32_e32 v6, 16, v6
	v_or_b32_e32 v7, v3, v122
	s_nop 0
	s_lshl_b64 s[50:51], s[28:29], 1
	s_add_u32 s50, s96, s50
	v_mul_u32_u24_e32 v3, 0x90, v3
	v_lshl_or_b32 v4, v0, 4, v4
	s_addc_u32 s51, s97, s51
	v_mov_b32_e32 v2, 0
	s_nop 0
	s_mov_b64 s[50:51], s[44:45]
	s_nop 0
	v_mov_b32_e32 v3, v2
	v_mov_b32_e32 v4, v2
	v_mov_b32_e32 v5, v2
	v_mov_b32_e32 v6, v2
	v_mov_b32_e32 v7, v2
	v_mov_b32_e32 v8, v2
	v_mov_b32_e32 v9, v2
	v_mov_b32_e32 v10, v2
	v_mov_b32_e32 v11, v2
	v_mov_b32_e32 v12, v2
	v_mov_b32_e32 v13, v2
	v_mov_b32_e32 v14, v2
	v_mov_b32_e32 v15, v2
	v_mov_b32_e32 v16, v2
	v_mov_b32_e32 v17, v2
	v_mov_b32_e32 v18, v2
	v_mov_b32_e32 v19, v2
	v_mov_b32_e32 v20, v2
	v_mov_b32_e32 v21, v2
	v_mov_b32_e32 v22, v2
	v_mov_b32_e32 v23, v2
	v_mov_b32_e32 v24, v2
	v_mov_b32_e32 v25, v2
	v_mov_b32_e32 v26, v2
	v_mov_b32_e32 v27, v2
	v_mov_b32_e32 v28, v2
	v_mov_b32_e32 v29, v2
	v_mov_b32_e32 v30, v2
	v_mov_b32_e32 v31, v2
	v_mov_b32_e32 v32, v2
	v_mov_b32_e32 v33, v2
	s_waitcnt vmcnt(12)
	v_mov_b32_e32 v34, v2
	v_mov_b32_e32 v35, v2
	v_mov_b32_e32 v36, v2
	v_mov_b32_e32 v37, v2
	s_waitcnt vmcnt(8)
	v_mov_b32_e32 v38, v2
	v_mov_b32_e32 v39, v2
	v_mov_b32_e32 v40, v2
	v_mov_b32_e32 v41, v2
	v_mov_b32_e32 v42, v2
	v_mov_b32_e32 v43, v2
	v_mov_b32_e32 v44, v2
	v_mov_b32_e32 v45, v2
	v_mov_b32_e32 v46, v2
	v_mov_b32_e32 v47, v2
	v_mov_b32_e32 v48, v2
	v_mov_b32_e32 v49, v2
	v_mov_b32_e32 v50, v2
	v_mov_b32_e32 v51, v2
	v_mov_b32_e32 v52, v2
	v_mov_b32_e32 v53, v2
	s_waitcnt vmcnt(8)
	v_mov_b32_e32 v54, v2
	v_mov_b32_e32 v55, v2
	v_mov_b32_e32 v56, v2
	v_mov_b32_e32 v57, v2
	v_mov_b32_e32 v58, v2
	v_mov_b32_e32 v59, v2
	v_mov_b32_e32 v60, v2
	v_mov_b32_e32 v61, v2
	v_mov_b32_e32 v62, v2
	v_mov_b32_e32 v63, v2
	v_mov_b32_e32 v64, v2
	v_mov_b32_e32 v65, v2
	s_movk_i32 s19, 7
; #define MFMA32(a, b, c) __builtin_amdgcn_mfma_f32_32x32x16_bf16((a), (b), (c), 0, 0, 0)
;     ...
;   for (int kt = 0; kt < NKT; ++kt) {
;     __syncthreads();
; #pragma unroll
;     for (int it = 0; it < 4; ++it) {
;       *(u32x4*)(Xs + (lr + 32 * it) * LSTR + lc) = xr[it];
;       *(u32x4*)(Ys + (lr + 32 * it) * LSTR + lc) = yr[it];
;     }
;     __syncthreads();
;     if (kt + 1 < NKT) {
; #pragma unroll
;       for (int it = 0; it < 4; ++it) {
;         xr[it] = *(const u32x4*)(xg + (size_t)it * 32 * RS + (kt + 1) * 64);
;         yr[it] = *(const u32x4*)(yg + (size_t)it * 32 * RS + (kt + 1) * 64);
;       }
;     }
; #pragma unroll
;     for (int ks = 0; ks < 4; ++ks) {
;       bf16x8 af[TI], bfr[TJ];
; #pragma unroll
;       for (int a = 0; a < TI; ++a) af[a] = *(const bf16x8*)(Xs + (wi0 + a * 32 + fr) * LSTR + ks * 16 + fh);
; #pragma unroll
;       for (int b = 0; b < TJ; ++b) bfr[b] = *(const bf16x8*)(Ys + (wj0 + b * 32 + fr) * LSTR + ks * 16 + fh);
; #pragma unroll
;       for (int a = 0; a < TI; ++a)
; #pragma unroll
;         for (int b = 0; b < TJ; ++b) acc[a][b] = MFMA32(af[a], bfr[b], acc[a][b]);
;     }
.Lwd_k_pq2:
	v_xor_b32_e32 v133, 0x40, v118
	s_waitcnt vmcnt(11)
	ds_write_b128 v118, v[70:73] offset:16384
	s_waitcnt vmcnt(10)
	ds_write_b128 v133, v[78:81] offset:17408
	s_waitcnt vmcnt(9)
	ds_write_b128 v118, v[86:89] offset:18432
	s_waitcnt vmcnt(8)
	ds_write_b128 v133, v[94:97] offset:19456
	s_waitcnt vmcnt(4)
	s_waitcnt lgkmcnt(0)
	s_barrier
	s_add_u32 s100, s100, 0x80
	s_addc_u32 s101, s101, 0
	s_mov_b32 m0, s41
	s_nop 0
	global_load_lds_dwordx4 v120, s[100:101]
	global_load_lds_dwordx4 v121, s[100:101] offset:1024
	v_add_u32_e32 v133, 0x7800, v120
	global_load_lds_dwordx4 v133, s[100:101] offset:2048
	v_add_u32_e32 v133, 0x7800, v121
	global_load_lds_dwordx4 v133, s[100:101] offset:3072
	ds_read_b128 v[134:137], v114 offset:4096
	ds_read_b128 v[138:141], v114 offset:8192
	ds_read_b128 v[142:145], v114 offset:12288
	ds_read_b128 v[148:151], v114
	ds_read_b128 v[152:155], v115
	v_add_u32_e32 v0, s32, v114
	ds_read_b128 v[160:163], v0 offset:16384
	v_add_u32_e32 v0, s32, v115
	ds_read_b128 v[156:159], v0 offset:16384
	s_waitcnt lgkmcnt(1)
	v_mfma_f32_32x32x16_bf16 v[34:49], v[134:137], v[160:163], v[34:49]
	ds_read_b128 v[134:137], v115 offset:4096
	v_mfma_f32_32x32x16_bf16 v[18:33], v[138:141], v[160:163], v[18:33]
	ds_read_b128 v[138:141], v115 offset:8192
	v_mfma_f32_32x32x16_bf16 v[2:17], v[142:145], v[160:163], v[2:17]
	ds_read_b128 v[142:145], v115 offset:12288
	s_waitcnt lgkmcnt(2)
	v_mfma_f32_32x32x16_bf16 v[34:49], v[134:137], v[156:159], v[34:49]
	ds_read_b128 v[134:137], v116
	s_waitcnt lgkmcnt(2)
	v_mfma_f32_32x32x16_bf16 v[18:33], v[138:141], v[156:159], v[18:33]
	ds_read_b128 v[138:141], v116 offset:4096
	s_waitcnt lgkmcnt(2)
	v_mfma_f32_32x32x16_bf16 v[2:17], v[142:145], v[156:159], v[2:17]
	ds_read_b128 v[142:145], v116 offset:8192
	v_mfma_f32_32x32x16_bf16 v[50:65], v[148:151], v[160:163], v[50:65]
	ds_read_b128 v[148:151], v116 offset:12288
	v_mfma_f32_32x32x16_bf16 v[50:65], v[152:155], v[156:159], v[50:65]
	v_add_u32_e32 v0, s32, v116
	ds_read_b128 v[152:155], v0 offset:16384
	s_waitcnt lgkmcnt(0)
	v_mfma_f32_32x32x16_bf16 v[50:65], v[134:137], v[152:155], v[50:65]
	ds_read_b128 v[134:137], v117
	v_mfma_f32_32x32x16_bf16 v[34:49], v[138:141], v[152:155], v[34:49]
	ds_read_b128 v[138:141], v117 offset:4096
	v_mfma_f32_32x32x16_bf16 v[18:33], v[142:145], v[152:155], v[18:33]
	ds_read_b128 v[142:145], v117 offset:8192
	v_mfma_f32_32x32x16_bf16 v[2:17], v[148:151], v[152:155], v[2:17]
	ds_read_b128 v[148:151], v117 offset:12288
	v_add_u32_e32 v0, s32, v117
	ds_read_b128 v[152:155], v0 offset:16384
	s_add_u32 s50, s50, 0x80
	s_addc_u32 s51, s51, 0
	global_load_dwordx4 v[70:73], v119, s[50:51] offset:128
	v_add_u32_e32 v133, 0x4000, v119
	global_load_dwordx4 v[78:81], v133, s[50:51] offset:128
	v_add_u32_e32 v133, 0x8000, v119
	global_load_dwordx4 v[86:89], v133, s[50:51] offset:128
	v_add_u32_e32 v133, 0xc000, v119
	global_load_dwordx4 v[94:97], v133, s[50:51] offset:128
	s_waitcnt lgkmcnt(0)
	v_mfma_f32_32x32x16_bf16 v[50:65], v[134:137], v[152:155], v[50:65]
	v_mfma_f32_32x32x16_bf16 v[34:49], v[138:141], v[152:155], v[34:49]
	v_mfma_f32_32x32x16_bf16 v[18:33], v[142:145], v[152:155], v[18:33]
	v_mfma_f32_32x32x16_bf16 v[2:17], v[148:151], v[152:155], v[2:17]
	v_xor_b32_e32 v133, 0x40, v118
	s_waitcnt vmcnt(11)
	ds_write_b128 v118, v[66:69] offset:16384
	s_waitcnt vmcnt(10)
	ds_write_b128 v133, v[74:77] offset:17408
	s_waitcnt vmcnt(9)
	ds_write_b128 v118, v[82:85] offset:18432
	s_waitcnt vmcnt(8)
	ds_write_b128 v133, v[90:93] offset:19456
	s_waitcnt vmcnt(4)
	s_waitcnt lgkmcnt(0)
	s_barrier
	s_add_u32 s100, s100, 0x80
	s_addc_u32 s101, s101, 0
	s_mov_b32 m0, s32
	s_nop 0
	global_load_lds_dwordx4 v120, s[100:101]
	global_load_lds_dwordx4 v121, s[100:101] offset:1024
	v_add_u32_e32 v133, 0x7800, v120
	global_load_lds_dwordx4 v133, s[100:101] offset:2048
	v_add_u32_e32 v133, 0x7800, v121
	global_load_lds_dwordx4 v133, s[100:101] offset:3072
	ds_read_b128 v[134:137], v114 offset:36864
	ds_read_b128 v[138:141], v114 offset:40992
	ds_read_b128 v[142:145], v114 offset:45088
	ds_read_b128 v[148:151], v114 offset:32768
	ds_read_b128 v[152:155], v115 offset:32768
	v_add_u32_e32 v0, s32, v114
	ds_read_b128 v[160:163], v0 offset:16384
	v_add_u32_e32 v0, s32, v115
	ds_read_b128 v[156:159], v0 offset:16384
	s_waitcnt lgkmcnt(1)
	v_mfma_f32_32x32x16_bf16 v[34:49], v[134:137], v[160:163], v[34:49]
	ds_read_b128 v[134:137], v115 offset:36864
	v_mfma_f32_32x32x16_bf16 v[18:33], v[138:141], v[160:163], v[18:33]
	ds_read_b128 v[138:141], v115 offset:40992
	v_mfma_f32_32x32x16_bf16 v[2:17], v[142:145], v[160:163], v[2:17]
	ds_read_b128 v[142:145], v115 offset:45088
	s_waitcnt lgkmcnt(2)
	v_mfma_f32_32x32x16_bf16 v[34:49], v[134:137], v[156:159], v[34:49]
	ds_read_b128 v[134:137], v116 offset:32768
	s_waitcnt lgkmcnt(2)
	v_mfma_f32_32x32x16_bf16 v[18:33], v[138:141], v[156:159], v[18:33]
	ds_read_b128 v[138:141], v116 offset:36864
	s_waitcnt lgkmcnt(2)
	v_mfma_f32_32x32x16_bf16 v[2:17], v[142:145], v[156:159], v[2:17]
	ds_read_b128 v[142:145], v116 offset:40992
	v_mfma_f32_32x32x16_bf16 v[50:65], v[148:151], v[160:163], v[50:65]
	ds_read_b128 v[148:151], v116 offset:45088
	v_mfma_f32_32x32x16_bf16 v[50:65], v[152:155], v[156:159], v[50:65]
	v_add_u32_e32 v0, s32, v116
	ds_read_b128 v[152:155], v0 offset:16384
	s_waitcnt lgkmcnt(0)
	v_mfma_f32_32x32x16_bf16 v[50:65], v[134:137], v[152:155], v[50:65]
	ds_read_b128 v[134:137], v117 offset:32768
	v_mfma_f32_32x32x16_bf16 v[34:49], v[138:141], v[152:155], v[34:49]
	ds_read_b128 v[138:141], v117 offset:36864
	v_mfma_f32_32x32x16_bf16 v[18:33], v[142:145], v[152:155], v[18:33]
	ds_read_b128 v[142:145], v117 offset:40992
	v_mfma_f32_32x32x16_bf16 v[2:17], v[148:151], v[152:155], v[2:17]
	ds_read_b128 v[148:151], v117 offset:45088
	v_add_u32_e32 v0, s32, v117
	ds_read_b128 v[152:155], v0 offset:16384
	s_add_u32 s50, s50, 0x80
	s_addc_u32 s51, s51, 0
	global_load_dwordx4 v[66:69], v119, s[50:51] offset:128
	v_add_u32_e32 v133, 0x4000, v119
	global_load_dwordx4 v[74:77], v133, s[50:51] offset:128
	v_add_u32_e32 v133, 0x8000, v119
	global_load_dwordx4 v[82:85], v133, s[50:51] offset:128
	v_add_u32_e32 v133, 0xc000, v119
	global_load_dwordx4 v[90:93], v133, s[50:51] offset:128
	s_waitcnt lgkmcnt(0)
	v_mfma_f32_32x32x16_bf16 v[50:65], v[134:137], v[152:155], v[50:65]
	v_mfma_f32_32x32x16_bf16 v[34:49], v[138:141], v[152:155], v[34:49]
	v_mfma_f32_32x32x16_bf16 v[18:33], v[142:145], v[152:155], v[18:33]
	v_mfma_f32_32x32x16_bf16 v[2:17], v[148:151], v[152:155], v[2:17]
	s_sub_u32 s19, s19, 1
	s_cmp_lg_u32 s19, 0
	s_cbranch_scc1 .Lwd_k_pq2
; #define MFMA32(a, b, c) __builtin_amdgcn_mfma_f32_32x32x16_bf16((a), (b), (c), 0, 0, 0)
;     ...
;   for (int kt = 0; kt < NKT; ++kt) {
;     __syncthreads();
; #pragma unroll
;     for (int it = 0; it < 4; ++it) {
;       *(u32x4*)(Xs + (lr + 32 * it) * LSTR + lc) = xr[it];
;       *(u32x4*)(Ys + (lr + 32 * it) * LSTR + lc) = yr[it];
;     }
;     __syncthreads();
;     if (kt + 1 < NKT) {
; #pragma unroll
;       for (int it = 0; it < 4; ++it) {
;         xr[it] = *(const u32x4*)(xg + (size_t)it * 32 * RS + (kt + 1) * 64);
;         yr[it] = *(const u32x4*)(yg + (size_t)it * 32 * RS + (kt + 1) * 64);
;       }
;     }
; #pragma unroll
;     for (int ks = 0; ks < 4; ++ks) {
;       bf16x8 af[TI], bfr[TJ];
; #pragma unroll
;       for (int a = 0; a < TI; ++a) af[a] = *(const bf16x8*)(Xs + (wi0 + a * 32 + fr) * LSTR + ks * 16 + fh);
; #pragma unroll
;       for (int b = 0; b < TJ; ++b) bfr[b] = *(const bf16x8*)(Ys + (wj0 + b * 32 + fr) * LSTR + ks * 16 + fh);
; #pragma unroll
;       for (int a = 0; a < TI; ++a)
; #pragma unroll
;         for (int b = 0; b < TJ; ++b) acc[a][b] = MFMA32(af[a], bfr[b], acc[a][b]);
;     }
	v_xor_b32_e32 v133, 0x40, v118
	s_waitcnt vmcnt(11)
	ds_write_b128 v118, v[70:73] offset:16384
	s_waitcnt vmcnt(10)
	ds_write_b128 v133, v[78:81] offset:17408
	s_waitcnt vmcnt(9)
	ds_write_b128 v118, v[86:89] offset:18432
	s_waitcnt vmcnt(8)
	ds_write_b128 v133, v[94:97] offset:19456
	s_waitcnt vmcnt(4)
	s_waitcnt lgkmcnt(0)
	s_barrier
	s_add_u32 s100, s100, 0x80
	s_addc_u32 s101, s101, 0
	s_mov_b32 m0, s41
	s_nop 0
	global_load_lds_dwordx4 v120, s[100:101]
	global_load_lds_dwordx4 v121, s[100:101] offset:1024
	v_add_u32_e32 v133, 0x7800, v120
	global_load_lds_dwordx4 v133, s[100:101] offset:2048
	v_add_u32_e32 v133, 0x7800, v121
	global_load_lds_dwordx4 v133, s[100:101] offset:3072
	ds_read_b128 v[134:137], v114 offset:4096
	ds_read_b128 v[138:141], v114 offset:8192
	ds_read_b128 v[142:145], v114 offset:12288
	ds_read_b128 v[148:151], v114
	ds_read_b128 v[152:155], v115
	v_add_u32_e32 v0, s32, v114
	ds_read_b128 v[160:163], v0 offset:16384
	v_add_u32_e32 v0, s32, v115
	ds_read_b128 v[156:159], v0 offset:16384
	s_waitcnt lgkmcnt(1)
	v_mfma_f32_32x32x16_bf16 v[34:49], v[134:137], v[160:163], v[34:49]
	ds_read_b128 v[134:137], v115 offset:4096
	v_mfma_f32_32x32x16_bf16 v[18:33], v[138:141], v[160:163], v[18:33]
	ds_read_b128 v[138:141], v115 offset:8192
	v_mfma_f32_32x32x16_bf16 v[2:17], v[142:145], v[160:163], v[2:17]
	ds_read_b128 v[142:145], v115 offset:12288
	s_waitcnt lgkmcnt(2)
	v_mfma_f32_32x32x16_bf16 v[34:49], v[134:137], v[156:159], v[34:49]
	ds_read_b128 v[134:137], v116
	s_waitcnt lgkmcnt(2)
	v_mfma_f32_32x32x16_bf16 v[18:33], v[138:141], v[156:159], v[18:33]
	ds_read_b128 v[138:141], v116 offset:4096
	s_waitcnt lgkmcnt(2)
	v_mfma_f32_32x32x16_bf16 v[2:17], v[142:145], v[156:159], v[2:17]
	ds_read_b128 v[142:145], v116 offset:8192
	v_mfma_f32_32x32x16_bf16 v[50:65], v[148:151], v[160:163], v[50:65]
	ds_read_b128 v[148:151], v116 offset:12288
	v_mfma_f32_32x32x16_bf16 v[50:65], v[152:155], v[156:159], v[50:65]
	v_add_u32_e32 v0, s32, v116
	ds_read_b128 v[152:155], v0 offset:16384
	s_waitcnt lgkmcnt(0)
	v_mfma_f32_32x32x16_bf16 v[50:65], v[134:137], v[152:155], v[50:65]
	ds_read_b128 v[134:137], v117
	v_mfma_f32_32x32x16_bf16 v[34:49], v[138:141], v[152:155], v[34:49]
	ds_read_b128 v[138:141], v117 offset:4096
	v_mfma_f32_32x32x16_bf16 v[18:33], v[142:145], v[152:155], v[18:33]
	ds_read_b128 v[142:145], v117 offset:8192
	v_mfma_f32_32x32x16_bf16 v[2:17], v[148:151], v[152:155], v[2:17]
	ds_read_b128 v[148:151], v117 offset:12288
	v_add_u32_e32 v0, s32, v117
	ds_read_b128 v[152:155], v0 offset:16384
	s_waitcnt lgkmcnt(0)
	v_mfma_f32_32x32x16_bf16 v[50:65], v[134:137], v[152:155], v[50:65]
	v_mfma_f32_32x32x16_bf16 v[34:49], v[138:141], v[152:155], v[34:49]
	v_mfma_f32_32x32x16_bf16 v[18:33], v[142:145], v[152:155], v[18:33]
	v_mfma_f32_32x32x16_bf16 v[2:17], v[148:151], v[152:155], v[2:17]
	v_xor_b32_e32 v133, 0x40, v118
	s_waitcnt vmcnt(7)
	ds_write_b128 v118, v[66:69] offset:16384
	s_waitcnt vmcnt(6)
	ds_write_b128 v133, v[74:77] offset:17408
	s_waitcnt vmcnt(5)
	ds_write_b128 v118, v[82:85] offset:18432
	s_waitcnt vmcnt(4)
	ds_write_b128 v133, v[90:93] offset:19456
	s_waitcnt vmcnt(0)
	s_waitcnt lgkmcnt(0)
	s_barrier
	ds_read_b128 v[134:137], v114 offset:36864
	ds_read_b128 v[138:141], v114 offset:40992
	ds_read_b128 v[142:145], v114 offset:45088
	ds_read_b128 v[148:151], v114 offset:32768
	ds_read_b128 v[152:155], v115 offset:32768
	v_add_u32_e32 v0, s32, v114
	ds_read_b128 v[160:163], v0 offset:16384
	v_add_u32_e32 v0, s32, v115
	ds_read_b128 v[156:159], v0 offset:16384
	s_waitcnt lgkmcnt(1)
	v_mfma_f32_32x32x16_bf16 v[34:49], v[134:137], v[160:163], v[34:49]
	ds_read_b128 v[134:137], v115 offset:36864
	v_mfma_f32_32x32x16_bf16 v[18:33], v[138:141], v[160:163], v[18:33]
	ds_read_b128 v[138:141], v115 offset:40992
	v_mfma_f32_32x32x16_bf16 v[2:17], v[142:145], v[160:163], v[2:17]
	ds_read_b128 v[142:145], v115 offset:45088
	s_waitcnt lgkmcnt(2)
	v_mfma_f32_32x32x16_bf16 v[34:49], v[134:137], v[156:159], v[34:49]
	ds_read_b128 v[134:137], v116 offset:32768
	s_waitcnt lgkmcnt(2)
	v_mfma_f32_32x32x16_bf16 v[18:33], v[138:141], v[156:159], v[18:33]
	ds_read_b128 v[138:141], v116 offset:36864
	s_waitcnt lgkmcnt(2)
	v_mfma_f32_32x32x16_bf16 v[2:17], v[142:145], v[156:159], v[2:17]
	ds_read_b128 v[142:145], v116 offset:40992
	v_mfma_f32_32x32x16_bf16 v[50:65], v[148:151], v[160:163], v[50:65]
	ds_read_b128 v[148:151], v116 offset:45088
	v_mfma_f32_32x32x16_bf16 v[50:65], v[152:155], v[156:159], v[50:65]
	v_add_u32_e32 v0, s32, v116
	ds_read_b128 v[152:155], v0 offset:16384
	s_waitcnt lgkmcnt(0)
	v_mfma_f32_32x32x16_bf16 v[50:65], v[134:137], v[152:155], v[50:65]
	ds_read_b128 v[134:137], v117 offset:32768
	v_mfma_f32_32x32x16_bf16 v[34:49], v[138:141], v[152:155], v[34:49]
	ds_read_b128 v[138:141], v117 offset:36864
	v_mfma_f32_32x32x16_bf16 v[18:33], v[142:145], v[152:155], v[18:33]
	ds_read_b128 v[142:145], v117 offset:40992
	v_mfma_f32_32x32x16_bf16 v[2:17], v[148:151], v[152:155], v[2:17]
	ds_read_b128 v[148:151], v117 offset:45088
	v_add_u32_e32 v0, s32, v117
	ds_read_b128 v[152:155], v0 offset:16384
	s_waitcnt lgkmcnt(0)
; DI void ins16n(float (&t)[16], float x, int nf) {
; #pragma unroll
;   for (int i = 15; i >= 1; --i)
;     if (i <= nf) t[i] = __builtin_amdgcn_fmed3f(t[i - 1], t[i], x);
;   t[0] = fmaxf(t[0], x);
; }
; DI void phase_peer_q(const Params& p, int layer, u16* lds, const int WAVE_S) {
;     ...
;       for (int nt = 0; nt < 4; ++nt)
; #pragma unroll
;         for (int i = 0; i < 16; ++i) {
;           const uint32_t n = nt * 32 + (i & 3) + 8 * (i >> 2) + 4 * h;
;           const float v = __uint_as_float((__float_as_uint(acc[nt][0][i]) & ~127u) | n);
;           ins16n(t, v, nt * 16 + i);
	v_mfma_f32_32x32x16_bf16 v[50:65], v[134:137], v[152:155], v[50:65]
	v_mfma_f32_32x32x16_bf16 v[34:49], v[138:141], v[152:155], v[34:49]
	v_mfma_f32_32x32x16_bf16 v[18:33], v[142:145], v[152:155], v[18:33]
	v_mfma_f32_32x32x16_bf16 v[2:17], v[148:151], v[152:155], v[2:17]
	s_nop 7
	s_nop 7
	s_andn2_b64 vcc, exec, s[48:49]
	v_and_or_b32 v0, v50, s88, v123
	v_max_f32_e32 v0, v0, v0
	v_or_b32_e32 v50, 1, v123
	v_max_f32_e32 v0, 0xff61b1e6, v0
	v_and_or_b32 v50, v51, s88, v50
	v_med3_f32 v51, v0, v50, s92
	v_max_f32_e32 v50, v50, v50
	v_max_f32_e32 v0, v0, v50
	v_or_b32_e32 v50, 2, v123
	v_and_or_b32 v50, v52, s88, v50
	v_med3_f32 v52, v51, v50, s92
	v_med3_f32 v51, v0, v51, v50
	v_max_f32_e32 v50, v50, v50
	v_max_f32_e32 v0, v0, v50
	v_or_b32_e32 v50, 3, v123
	v_and_or_b32 v50, v53, s88, v50
	v_med3_f32 v53, v52, v50, s92
	v_med3_f32 v52, v51, v52, v50
	v_med3_f32 v51, v0, v51, v50
	v_max_f32_e32 v50, v50, v50
	v_max_f32_e32 v0, v0, v50
	v_or_b32_e32 v50, 8, v123
	v_and_or_b32 v50, v54, s88, v50
	v_med3_f32 v54, v53, v50, s92
	v_med3_f32 v53, v52, v53, v50
	v_med3_f32 v52, v51, v52, v50
	v_med3_f32 v51, v0, v51, v50
	v_max_f32_e32 v50, v50, v50
	v_max_f32_e32 v0, v0, v50
	v_or_b32_e32 v50, 9, v123
	v_and_or_b32 v50, v55, s88, v50
	v_med3_f32 v55, v54, v50, s92
	v_med3_f32 v54, v53, v54, v50
	v_med3_f32 v53, v52, v53, v50
	v_med3_f32 v52, v51, v52, v50
	v_med3_f32 v51, v0, v51, v50
	v_max_f32_e32 v50, v50, v50
	v_max_f32_e32 v0, v0, v50
	v_or_b32_e32 v50, 10, v123
	v_and_or_b32 v50, v56, s88, v50
	v_med3_f32 v56, v55, v50, s92
	v_med3_f32 v55, v54, v55, v50
	v_med3_f32 v54, v53, v54, v50
	v_med3_f32 v53, v52, v53, v50
	v_med3_f32 v52, v51, v52, v50
	v_med3_f32 v51, v0, v51, v50
	v_max_f32_e32 v50, v50, v50
	v_max_f32_e32 v0, v0, v50
	v_or_b32_e32 v50, 11, v123
	v_and_or_b32 v50, v57, s88, v50
	v_med3_f32 v57, v56, v50, s92
	v_med3_f32 v56, v55, v56, v50
	v_med3_f32 v55, v54, v55, v50
	v_med3_f32 v54, v53, v54, v50
	v_med3_f32 v53, v52, v53, v50
	v_med3_f32 v52, v51, v52, v50
	v_med3_f32 v51, v0, v51, v50
	v_max_f32_e32 v50, v50, v50
	v_max_f32_e32 v0, v0, v50
	v_or_b32_e32 v50, 16, v123
	v_and_or_b32 v50, v58, s88, v50
	v_med3_f32 v58, v57, v50, s92
	v_med3_f32 v57, v56, v57, v50
	v_med3_f32 v56, v55, v56, v50
	v_med3_f32 v55, v54, v55, v50
	v_med3_f32 v54, v53, v54, v50
	v_med3_f32 v53, v52, v53, v50
	v_med3_f32 v52, v51, v52, v50
	v_med3_f32 v51, v0, v51, v50
	v_max_f32_e32 v50, v50, v50
	v_max_f32_e32 v0, v0, v50
	v_or_b32_e32 v50, 17, v123
	v_and_or_b32 v50, v59, s88, v50
	v_med3_f32 v59, v58, v50, s92
	v_med3_f32 v58, v57, v58, v50
	v_med3_f32 v57, v56, v57, v50
	v_med3_f32 v56, v55, v56, v50
	v_med3_f32 v55, v54, v55, v50
	v_med3_f32 v54, v53, v54, v50
	v_med3_f32 v53, v52, v53, v50
	v_med3_f32 v52, v51, v52, v50
	v_med3_f32 v51, v0, v51, v50
	v_max_f32_e32 v50, v50, v50
	v_max_f32_e32 v0, v0, v50
	v_or_b32_e32 v50, 18, v123
	v_and_or_b32 v50, v60, s88, v50
	v_med3_f32 v60, v59, v50, s92
	v_med3_f32 v59, v58, v59, v50
	v_med3_f32 v58, v57, v58, v50
	v_med3_f32 v57, v56, v57, v50
	v_med3_f32 v56, v55, v56, v50
	v_med3_f32 v55, v54, v55, v50
	v_med3_f32 v54, v53, v54, v50
	v_med3_f32 v53, v52, v53, v50
	v_med3_f32 v52, v51, v52, v50
	v_med3_f32 v51, v0, v51, v50
	v_max_f32_e32 v50, v50, v50
	v_max_f32_e32 v0, v0, v50
	v_or_b32_e32 v50, 19, v123
	v_and_or_b32 v50, v61, s88, v50
	v_med3_f32 v61, v60, v50, s92
	v_med3_f32 v60, v59, v60, v50
	v_med3_f32 v59, v58, v59, v50
	v_med3_f32 v58, v57, v58, v50
	v_med3_f32 v57, v56, v57, v50
	v_med3_f32 v56, v55, v56, v50
	v_med3_f32 v55, v54, v55, v50
	v_med3_f32 v54, v53, v54, v50
	v_med3_f32 v53, v52, v53, v50
	v_med3_f32 v52, v51, v52, v50
	v_med3_f32 v51, v0, v51, v50
	v_max_f32_e32 v50, v50, v50
	v_max_f32_e32 v0, v0, v50
	v_or_b32_e32 v50, 24, v123
	v_and_or_b32 v50, v62, s88, v50
	v_med3_f32 v62, v61, v50, s92
	v_med3_f32 v61, v60, v61, v50
	v_med3_f32 v60, v59, v60, v50
	v_med3_f32 v59, v58, v59, v50
	v_med3_f32 v58, v57, v58, v50
	v_med3_f32 v57, v56, v57, v50
	v_med3_f32 v56, v55, v56, v50
	v_med3_f32 v55, v54, v55, v50
	v_med3_f32 v54, v53, v54, v50
	v_med3_f32 v53, v52, v53, v50
	v_med3_f32 v52, v51, v52, v50
	v_med3_f32 v51, v0, v51, v50
	v_max_f32_e32 v50, v50, v50
	v_max_f32_e32 v0, v0, v50
	v_or_b32_e32 v50, 25, v123
	v_and_or_b32 v50, v63, s88, v50
	v_med3_f32 v63, v62, v50, s92
	v_med3_f32 v62, v61, v62, v50
	v_med3_f32 v61, v60, v61, v50
	v_med3_f32 v60, v59, v60, v50
	v_med3_f32 v59, v58, v59, v50
	v_med3_f32 v58, v57, v58, v50
	v_med3_f32 v57, v56, v57, v50
	v_med3_f32 v56, v55, v56, v50
	v_med3_f32 v55, v54, v55, v50
	v_med3_f32 v54, v53, v54, v50
	v_med3_f32 v53, v52, v53, v50
	v_med3_f32 v52, v51, v52, v50
	v_med3_f32 v51, v0, v51, v50
	v_max_f32_e32 v50, v50, v50
	v_max_f32_e32 v0, v0, v50
	v_or_b32_e32 v50, 26, v123
	v_and_or_b32 v50, v64, s88, v50
	v_med3_f32 v64, v63, v50, s92
	v_med3_f32 v63, v62, v63, v50
	v_med3_f32 v62, v61, v62, v50
	v_med3_f32 v61, v60, v61, v50
	v_med3_f32 v60, v59, v60, v50
	v_med3_f32 v59, v58, v59, v50
	v_med3_f32 v58, v57, v58, v50
	v_med3_f32 v57, v56, v57, v50
	v_med3_f32 v56, v55, v56, v50
	v_med3_f32 v55, v54, v55, v50
	v_med3_f32 v54, v53, v54, v50
	v_med3_f32 v53, v52, v53, v50
	v_med3_f32 v52, v51, v52, v50
	v_med3_f32 v51, v0, v51, v50
	v_max_f32_e32 v50, v50, v50
	v_max_f32_e32 v0, v0, v50
	v_or_b32_e32 v50, 27, v123
	v_and_or_b32 v50, v65, s88, v50
	v_med3_f32 v65, v64, v50, s92
	v_med3_f32 v64, v63, v64, v50
	v_med3_f32 v63, v62, v63, v50
	v_med3_f32 v62, v61, v62, v50
	v_med3_f32 v61, v60, v61, v50
	v_med3_f32 v60, v59, v60, v50
	v_med3_f32 v59, v58, v59, v50
	v_med3_f32 v58, v57, v58, v50
	v_med3_f32 v57, v56, v57, v50
; DI void ins16n(float (&t)[16], float x, int nf) {
; #pragma unroll
;   for (int i = 15; i >= 1; --i)
;     if (i <= nf) t[i] = __builtin_amdgcn_fmed3f(t[i - 1], t[i], x);
;   t[0] = fmaxf(t[0], x);
; }
; DI void phase_peer_q(const Params& p, int layer, u16* lds, const int WAVE_S) {
;     ...
;       for (int nt = 0; nt < 4; ++nt)
; #pragma unroll
;         for (int i = 0; i < 16; ++i) {
;           const uint32_t n = nt * 32 + (i & 3) + 8 * (i >> 2) + 4 * h;
;           const float v = __uint_as_float((__float_as_uint(acc[nt][0][i]) & ~127u) | n);
;           ins16n(t, v, nt * 16 + i);
	v_med3_f32 v56, v55, v56, v50
	v_med3_f32 v55, v54, v55, v50
	v_med3_f32 v54, v53, v54, v50
	v_med3_f32 v53, v52, v53, v50
	v_med3_f32 v52, v51, v52, v50
	v_med3_f32 v51, v0, v51, v50
	v_max_f32_e32 v50, v50, v50
	v_max_f32_e32 v0, v0, v50
	v_or_b32_e32 v50, 32, v123
	v_and_or_b32 v34, v34, s88, v50
	v_med3_f32 v50, v64, v65, v34
	v_med3_f32 v64, v63, v64, v34
	v_med3_f32 v63, v62, v63, v34
	v_med3_f32 v62, v61, v62, v34
	v_med3_f32 v61, v60, v61, v34
	v_med3_f32 v60, v59, v60, v34
	v_med3_f32 v59, v58, v59, v34
	v_med3_f32 v58, v57, v58, v34
	v_med3_f32 v57, v56, v57, v34
	v_med3_f32 v56, v55, v56, v34
	v_med3_f32 v55, v54, v55, v34
	v_med3_f32 v54, v53, v54, v34
	v_med3_f32 v53, v52, v53, v34
	v_med3_f32 v52, v51, v52, v34
	v_med3_f32 v51, v0, v51, v34
	v_max_f32_e32 v34, v34, v34
	v_max_f32_e32 v0, v0, v34
	v_or_b32_e32 v34, 33, v123
	v_and_or_b32 v34, v35, s88, v34
	v_med3_f32 v35, v64, v50, v34
	v_med3_f32 v50, v63, v64, v34
	v_med3_f32 v63, v62, v63, v34
	v_med3_f32 v62, v61, v62, v34
	v_med3_f32 v61, v60, v61, v34
	v_med3_f32 v60, v59, v60, v34
	v_med3_f32 v59, v58, v59, v34
	v_med3_f32 v58, v57, v58, v34
	v_med3_f32 v57, v56, v57, v34
	v_med3_f32 v56, v55, v56, v34
	v_med3_f32 v55, v54, v55, v34
	v_med3_f32 v54, v53, v54, v34
	v_med3_f32 v53, v52, v53, v34
	v_med3_f32 v52, v51, v52, v34
	v_med3_f32 v51, v0, v51, v34
	v_max_f32_e32 v34, v34, v34
	v_max_f32_e32 v0, v0, v34
	v_or_b32_e32 v34, 34, v123
	v_and_or_b32 v34, v36, s88, v34
	v_med3_f32 v35, v50, v35, v34
	v_med3_f32 v36, v63, v50, v34
	v_med3_f32 v50, v62, v63, v34
	v_med3_f32 v62, v61, v62, v34
	v_med3_f32 v61, v60, v61, v34
	v_med3_f32 v60, v59, v60, v34
	v_med3_f32 v59, v58, v59, v34
	v_med3_f32 v58, v57, v58, v34
	v_med3_f32 v57, v56, v57, v34
	v_med3_f32 v56, v55, v56, v34
	v_med3_f32 v55, v54, v55, v34
	v_med3_f32 v54, v53, v54, v34
	v_med3_f32 v53, v52, v53, v34
	v_med3_f32 v52, v51, v52, v34
	v_med3_f32 v51, v0, v51, v34
	v_max_f32_e32 v34, v34, v34
	v_max_f32_e32 v0, v0, v34
	v_or_b32_e32 v34, 35, v123
	v_and_or_b32 v34, v37, s88, v34
	v_med3_f32 v35, v36, v35, v34
	v_med3_f32 v36, v50, v36, v34
	v_med3_f32 v37, v62, v50, v34
	v_med3_f32 v50, v61, v62, v34
	v_med3_f32 v61, v60, v61, v34
	v_med3_f32 v60, v59, v60, v34
	v_med3_f32 v59, v58, v59, v34
	v_med3_f32 v58, v57, v58, v34
	v_med3_f32 v57, v56, v57, v34
	v_med3_f32 v56, v55, v56, v34
	v_med3_f32 v55, v54, v55, v34
	v_med3_f32 v54, v53, v54, v34
	v_med3_f32 v53, v52, v53, v34
	v_med3_f32 v52, v51, v52, v34
	v_med3_f32 v51, v0, v51, v34
	v_max_f32_e32 v34, v34, v34
	v_max_f32_e32 v0, v0, v34
	v_or_b32_e32 v34, 40, v123
	v_and_or_b32 v34, v38, s88, v34
	v_med3_f32 v35, v36, v35, v34
	v_med3_f32 v36, v37, v36, v34
	v_med3_f32 v37, v50, v37, v34
	v_med3_f32 v38, v61, v50, v34
	v_med3_f32 v50, v60, v61, v34
	v_med3_f32 v60, v59, v60, v34
	v_med3_f32 v59, v58, v59, v34
	v_med3_f32 v58, v57, v58, v34
	v_med3_f32 v57, v56, v57, v34
	v_med3_f32 v56, v55, v56, v34
	v_med3_f32 v55, v54, v55, v34
	v_med3_f32 v54, v53, v54, v34
	v_med3_f32 v53, v52, v53, v34
	v_med3_f32 v52, v51, v52, v34
	v_med3_f32 v51, v0, v51, v34
	v_max_f32_e32 v34, v34, v34
	v_max_f32_e32 v0, v0, v34
	v_or_b32_e32 v34, 41, v123
	v_and_or_b32 v34, v39, s88, v34
	v_med3_f32 v35, v36, v35, v34
	v_med3_f32 v36, v37, v36, v34
	v_med3_f32 v37, v38, v37, v34
	v_med3_f32 v38, v50, v38, v34
	v_med3_f32 v39, v60, v50, v34
	v_med3_f32 v50, v59, v60, v34
	v_med3_f32 v59, v58, v59, v34
	v_med3_f32 v58, v57, v58, v34
	v_med3_f32 v57, v56, v57, v34
	v_med3_f32 v56, v55, v56, v34
	v_med3_f32 v55, v54, v55, v34
	v_med3_f32 v54, v53, v54, v34
	v_med3_f32 v53, v52, v53, v34
	v_med3_f32 v52, v51, v52, v34
	v_med3_f32 v51, v0, v51, v34
	v_max_f32_e32 v34, v34, v34
	v_max_f32_e32 v0, v0, v34
	v_or_b32_e32 v34, 42, v123
	v_and_or_b32 v34, v40, s88, v34
	v_med3_f32 v35, v36, v35, v34
	v_med3_f32 v36, v37, v36, v34
	v_med3_f32 v37, v38, v37, v34
	v_med3_f32 v38, v39, v38, v34
	v_med3_f32 v39, v50, v39, v34
	v_med3_f32 v40, v59, v50, v34
	v_med3_f32 v50, v58, v59, v34
	v_med3_f32 v58, v57, v58, v34
	v_med3_f32 v57, v56, v57, v34
	v_med3_f32 v56, v55, v56, v34
	v_med3_f32 v55, v54, v55, v34
	v_med3_f32 v54, v53, v54, v34
	v_med3_f32 v53, v52, v53, v34
	v_med3_f32 v52, v51, v52, v34
	v_med3_f32 v51, v0, v51, v34
	v_max_f32_e32 v34, v34, v34
	v_max_f32_e32 v0, v0, v34
	v_or_b32_e32 v34, 43, v123
	v_and_or_b32 v34, v41, s88, v34
	v_med3_f32 v35, v36, v35, v34
	v_med3_f32 v36, v37, v36, v34
	v_med3_f32 v37, v38, v37, v34
	v_med3_f32 v38, v39, v38, v34
	v_med3_f32 v39, v40, v39, v34
	v_med3_f32 v40, v50, v40, v34
	v_med3_f32 v41, v58, v50, v34
	v_med3_f32 v50, v57, v58, v34
	v_med3_f32 v57, v56, v57, v34
	v_med3_f32 v56, v55, v56, v34
	v_med3_f32 v55, v54, v55, v34
	v_med3_f32 v54, v53, v54, v34
	v_med3_f32 v53, v52, v53, v34
	v_med3_f32 v52, v51, v52, v34
	v_med3_f32 v51, v0, v51, v34
	v_max_f32_e32 v34, v34, v34
	v_max_f32_e32 v0, v0, v34
	v_or_b32_e32 v34, 48, v123
	v_and_or_b32 v34, v42, s88, v34
	v_med3_f32 v35, v36, v35, v34
	v_med3_f32 v36, v37, v36, v34
	v_med3_f32 v37, v38, v37, v34
	v_med3_f32 v38, v39, v38, v34
	v_med3_f32 v39, v40, v39, v34
	v_med3_f32 v40, v41, v40, v34
	v_med3_f32 v41, v50, v41, v34
	v_med3_f32 v42, v57, v50, v34
	v_med3_f32 v50, v56, v57, v34
	v_med3_f32 v56, v55, v56, v34
	v_med3_f32 v55, v54, v55, v34
	v_med3_f32 v54, v53, v54, v34
	v_med3_f32 v53, v52, v53, v34
	v_med3_f32 v52, v51, v52, v34
	v_med3_f32 v51, v0, v51, v34
	v_max_f32_e32 v34, v34, v34
	v_max_f32_e32 v0, v0, v34
	v_or_b32_e32 v34, 49, v123
	v_and_or_b32 v34, v43, s88, v34
	v_med3_f32 v35, v36, v35, v34
	v_med3_f32 v36, v37, v36, v34
	v_med3_f32 v37, v38, v37, v34
	v_med3_f32 v38, v39, v38, v34
; DI void ins16n(float (&t)[16], float x, int nf) {
; #pragma unroll
;   for (int i = 15; i >= 1; --i)
;     if (i <= nf) t[i] = __builtin_amdgcn_fmed3f(t[i - 1], t[i], x);
;   t[0] = fmaxf(t[0], x);
; }
; DI void phase_peer_q(const Params& p, int layer, u16* lds, const int WAVE_S) {
;     ...
;       for (int nt = 0; nt < 4; ++nt)
; #pragma unroll
;         for (int i = 0; i < 16; ++i) {
;           const uint32_t n = nt * 32 + (i & 3) + 8 * (i >> 2) + 4 * h;
;           const float v = __uint_as_float((__float_as_uint(acc[nt][0][i]) & ~127u) | n);
;           ins16n(t, v, nt * 16 + i);
	v_med3_f32 v39, v40, v39, v34
	v_med3_f32 v40, v41, v40, v34
	v_med3_f32 v41, v42, v41, v34
	v_med3_f32 v42, v50, v42, v34
	v_med3_f32 v43, v56, v50, v34
	v_med3_f32 v50, v55, v56, v34
	v_med3_f32 v55, v54, v55, v34
	v_med3_f32 v54, v53, v54, v34
	v_med3_f32 v53, v52, v53, v34
	v_med3_f32 v52, v51, v52, v34
	v_med3_f32 v51, v0, v51, v34
	v_max_f32_e32 v34, v34, v34
	v_max_f32_e32 v0, v0, v34
	v_or_b32_e32 v34, 50, v123
	v_and_or_b32 v34, v44, s88, v34
	v_med3_f32 v35, v36, v35, v34
	v_med3_f32 v36, v37, v36, v34
	v_med3_f32 v37, v38, v37, v34
	v_med3_f32 v38, v39, v38, v34
	v_med3_f32 v39, v40, v39, v34
	v_med3_f32 v40, v41, v40, v34
	v_med3_f32 v41, v42, v41, v34
	v_med3_f32 v42, v43, v42, v34
	v_med3_f32 v43, v50, v43, v34
	v_med3_f32 v44, v55, v50, v34
	v_med3_f32 v50, v54, v55, v34
	v_med3_f32 v54, v53, v54, v34
	v_med3_f32 v53, v52, v53, v34
	v_med3_f32 v52, v51, v52, v34
	v_med3_f32 v51, v0, v51, v34
	v_max_f32_e32 v34, v34, v34
	v_max_f32_e32 v0, v0, v34
	v_or_b32_e32 v34, 51, v123
	v_and_or_b32 v34, v45, s88, v34
	v_med3_f32 v35, v36, v35, v34
	v_med3_f32 v36, v37, v36, v34
	v_med3_f32 v37, v38, v37, v34
	v_med3_f32 v38, v39, v38, v34
	v_med3_f32 v39, v40, v39, v34
	v_med3_f32 v40, v41, v40, v34
	v_med3_f32 v41, v42, v41, v34
	v_med3_f32 v42, v43, v42, v34
	v_med3_f32 v43, v44, v43, v34
	v_med3_f32 v44, v50, v44, v34
	v_med3_f32 v45, v54, v50, v34
	v_med3_f32 v50, v53, v54, v34
	v_med3_f32 v53, v52, v53, v34
	v_med3_f32 v52, v51, v52, v34
	v_med3_f32 v51, v0, v51, v34
	v_max_f32_e32 v34, v34, v34
	v_max_f32_e32 v0, v0, v34
	v_or_b32_e32 v34, 56, v123
	v_and_or_b32 v34, v46, s88, v34
	v_med3_f32 v35, v36, v35, v34
	v_med3_f32 v36, v37, v36, v34
	v_med3_f32 v37, v38, v37, v34
	v_med3_f32 v38, v39, v38, v34
	v_med3_f32 v39, v40, v39, v34
	v_med3_f32 v40, v41, v40, v34
	v_med3_f32 v41, v42, v41, v34
	v_med3_f32 v42, v43, v42, v34
	v_med3_f32 v43, v44, v43, v34
	v_med3_f32 v44, v45, v44, v34
	v_med3_f32 v45, v50, v45, v34
	v_med3_f32 v46, v53, v50, v34
	v_med3_f32 v50, v52, v53, v34
	v_med3_f32 v52, v51, v52, v34
	v_med3_f32 v51, v0, v51, v34
	v_max_f32_e32 v34, v34, v34
	v_max_f32_e32 v0, v0, v34
	v_or_b32_e32 v34, 57, v123
	v_and_or_b32 v34, v47, s88, v34
	v_med3_f32 v35, v36, v35, v34
	v_med3_f32 v36, v37, v36, v34
	v_med3_f32 v37, v38, v37, v34
	v_med3_f32 v38, v39, v38, v34
	v_med3_f32 v39, v40, v39, v34
	v_med3_f32 v40, v41, v40, v34
	v_med3_f32 v41, v42, v41, v34
	v_med3_f32 v42, v43, v42, v34
	v_med3_f32 v43, v44, v43, v34
	v_med3_f32 v44, v45, v44, v34
	v_med3_f32 v45, v46, v45, v34
	v_med3_f32 v46, v50, v46, v34
	v_med3_f32 v47, v52, v50, v34
	v_med3_f32 v50, v51, v52, v34
	v_med3_f32 v51, v0, v51, v34
	v_max_f32_e32 v34, v34, v34
	v_max_f32_e32 v0, v0, v34
	v_or_b32_e32 v34, 58, v123
	v_and_or_b32 v34, v48, s88, v34
	v_med3_f32 v35, v36, v35, v34
	v_med3_f32 v36, v37, v36, v34
	v_med3_f32 v37, v38, v37, v34
	v_med3_f32 v38, v39, v38, v34
	v_med3_f32 v39, v40, v39, v34
	v_med3_f32 v40, v41, v40, v34
	v_med3_f32 v41, v42, v41, v34
	v_med3_f32 v42, v43, v42, v34
	v_med3_f32 v43, v44, v43, v34
	v_med3_f32 v44, v45, v44, v34
	v_med3_f32 v45, v46, v45, v34
	v_med3_f32 v46, v47, v46, v34
	v_med3_f32 v47, v50, v47, v34
	v_med3_f32 v48, v51, v50, v34
	v_med3_f32 v50, v0, v51, v34
	v_max_f32_e32 v34, v34, v34
	v_max_f32_e32 v0, v0, v34
	v_or_b32_e32 v34, 59, v123
	v_and_or_b32 v34, v49, s88, v34
	v_med3_f32 v35, v36, v35, v34
	v_med3_f32 v36, v37, v36, v34
	v_med3_f32 v37, v38, v37, v34
	v_med3_f32 v38, v39, v38, v34
	v_med3_f32 v39, v40, v39, v34
	v_med3_f32 v40, v41, v40, v34
	v_med3_f32 v41, v42, v41, v34
	v_med3_f32 v42, v43, v42, v34
	v_med3_f32 v43, v44, v43, v34
	v_med3_f32 v44, v45, v44, v34
	v_med3_f32 v45, v46, v45, v34
	v_med3_f32 v46, v47, v46, v34
	v_med3_f32 v47, v48, v47, v34
	v_med3_f32 v48, v50, v48, v34
	v_med3_f32 v49, v0, v50, v34
	v_max_f32_e32 v34, v34, v34
	v_max_f32_e32 v0, v0, v34
	v_or_b32_e32 v34, 64, v123
	v_and_or_b32 v18, v18, s88, v34
	v_med3_f32 v34, v36, v35, v18
	v_med3_f32 v35, v37, v36, v18
	v_med3_f32 v36, v38, v37, v18
	v_med3_f32 v37, v39, v38, v18
	v_med3_f32 v38, v40, v39, v18
	v_med3_f32 v39, v41, v40, v18
	v_med3_f32 v40, v42, v41, v18
	v_med3_f32 v41, v43, v42, v18
	v_med3_f32 v42, v44, v43, v18
	v_med3_f32 v43, v45, v44, v18
	v_med3_f32 v44, v46, v45, v18
	v_med3_f32 v45, v47, v46, v18
	v_med3_f32 v46, v48, v47, v18
	v_med3_f32 v47, v49, v48, v18
	v_med3_f32 v48, v0, v49, v18
	v_max_f32_e32 v18, v18, v18
	v_max_f32_e32 v0, v0, v18
	v_or_b32_e32 v18, 0x41, v123
	v_and_or_b32 v18, v19, s88, v18
	v_med3_f32 v19, v35, v34, v18
	v_med3_f32 v34, v36, v35, v18
	v_med3_f32 v35, v37, v36, v18
	v_med3_f32 v36, v38, v37, v18
	v_med3_f32 v37, v39, v38, v18
	v_med3_f32 v38, v40, v39, v18
	v_med3_f32 v39, v41, v40, v18
	v_med3_f32 v40, v42, v41, v18
	v_med3_f32 v41, v43, v42, v18
	v_med3_f32 v42, v44, v43, v18
	v_med3_f32 v43, v45, v44, v18
	v_med3_f32 v44, v46, v45, v18
	v_med3_f32 v45, v47, v46, v18
	v_med3_f32 v46, v48, v47, v18
	v_med3_f32 v47, v0, v48, v18
	v_max_f32_e32 v18, v18, v18
	v_max_f32_e32 v0, v0, v18
	v_or_b32_e32 v18, 0x42, v123
	v_and_or_b32 v18, v20, s88, v18
	v_med3_f32 v19, v34, v19, v18
	v_med3_f32 v20, v35, v34, v18
	v_med3_f32 v34, v36, v35, v18
	v_med3_f32 v35, v37, v36, v18
	v_med3_f32 v36, v38, v37, v18
	v_med3_f32 v37, v39, v38, v18
	v_med3_f32 v38, v40, v39, v18
	v_med3_f32 v39, v41, v40, v18
	v_med3_f32 v40, v42, v41, v18
	v_med3_f32 v41, v43, v42, v18
	v_med3_f32 v42, v44, v43, v18
	v_med3_f32 v43, v45, v44, v18
	v_med3_f32 v44, v46, v45, v18
	v_med3_f32 v45, v47, v46, v18
	v_med3_f32 v46, v0, v47, v18
	v_max_f32_e32 v18, v18, v18
	v_max_f32_e32 v0, v0, v18
; DI void ins16n(float (&t)[16], float x, int nf) {
; #pragma unroll
;   for (int i = 15; i >= 1; --i)
;     if (i <= nf) t[i] = __builtin_amdgcn_fmed3f(t[i - 1], t[i], x);
;   t[0] = fmaxf(t[0], x);
; }
; DI void phase_peer_q(const Params& p, int layer, u16* lds, const int WAVE_S) {
;     ...
;       for (int nt = 0; nt < 4; ++nt)
; #pragma unroll
;         for (int i = 0; i < 16; ++i) {
;           const uint32_t n = nt * 32 + (i & 3) + 8 * (i >> 2) + 4 * h;
;           const float v = __uint_as_float((__float_as_uint(acc[nt][0][i]) & ~127u) | n);
;           ins16n(t, v, nt * 16 + i);
	v_or_b32_e32 v18, 0x43, v123
	v_and_or_b32 v18, v21, s88, v18
	v_med3_f32 v19, v20, v19, v18
	v_med3_f32 v20, v34, v20, v18
	v_med3_f32 v21, v35, v34, v18
	v_med3_f32 v34, v36, v35, v18
	v_med3_f32 v35, v37, v36, v18
	v_med3_f32 v36, v38, v37, v18
	v_med3_f32 v37, v39, v38, v18
	v_med3_f32 v38, v40, v39, v18
	v_med3_f32 v39, v41, v40, v18
	v_med3_f32 v40, v42, v41, v18
	v_med3_f32 v41, v43, v42, v18
	v_med3_f32 v42, v44, v43, v18
	v_med3_f32 v43, v45, v44, v18
	v_med3_f32 v44, v46, v45, v18
	v_med3_f32 v45, v0, v46, v18
	v_max_f32_e32 v18, v18, v18
	v_max_f32_e32 v0, v0, v18
	v_or_b32_e32 v18, 0x48, v123
	v_and_or_b32 v18, v22, s88, v18
	v_med3_f32 v19, v20, v19, v18
	v_med3_f32 v20, v21, v20, v18
	v_med3_f32 v21, v34, v21, v18
	v_med3_f32 v22, v35, v34, v18
	v_med3_f32 v34, v36, v35, v18
	v_med3_f32 v35, v37, v36, v18
	v_med3_f32 v36, v38, v37, v18
	v_med3_f32 v37, v39, v38, v18
	v_med3_f32 v38, v40, v39, v18
	v_med3_f32 v39, v41, v40, v18
	v_med3_f32 v40, v42, v41, v18
	v_med3_f32 v41, v43, v42, v18
	v_med3_f32 v42, v44, v43, v18
	v_med3_f32 v43, v45, v44, v18
	v_med3_f32 v44, v0, v45, v18
	v_max_f32_e32 v18, v18, v18
	v_max_f32_e32 v0, v0, v18
	v_or_b32_e32 v18, 0x49, v123
	v_and_or_b32 v18, v23, s88, v18
	v_med3_f32 v19, v20, v19, v18
	v_med3_f32 v20, v21, v20, v18
	v_med3_f32 v21, v22, v21, v18
	v_med3_f32 v22, v34, v22, v18
	v_med3_f32 v23, v35, v34, v18
	v_med3_f32 v34, v36, v35, v18
	v_med3_f32 v35, v37, v36, v18
	v_med3_f32 v36, v38, v37, v18
	v_med3_f32 v37, v39, v38, v18
	v_med3_f32 v38, v40, v39, v18
	v_med3_f32 v39, v41, v40, v18
	v_med3_f32 v40, v42, v41, v18
	v_med3_f32 v41, v43, v42, v18
	v_med3_f32 v42, v44, v43, v18
	v_med3_f32 v43, v0, v44, v18
	v_max_f32_e32 v18, v18, v18
	v_max_f32_e32 v0, v0, v18
	v_or_b32_e32 v18, 0x4a, v123
	v_and_or_b32 v18, v24, s88, v18
	v_med3_f32 v19, v20, v19, v18
	v_med3_f32 v20, v21, v20, v18
	v_med3_f32 v21, v22, v21, v18
	v_med3_f32 v22, v23, v22, v18
	v_med3_f32 v23, v34, v23, v18
	v_med3_f32 v24, v35, v34, v18
	v_med3_f32 v34, v36, v35, v18
	v_med3_f32 v35, v37, v36, v18
	v_med3_f32 v36, v38, v37, v18
	v_med3_f32 v37, v39, v38, v18
	v_med3_f32 v38, v40, v39, v18
	v_med3_f32 v39, v41, v40, v18
	v_med3_f32 v40, v42, v41, v18
	v_med3_f32 v41, v43, v42, v18
	v_med3_f32 v42, v0, v43, v18
	v_max_f32_e32 v18, v18, v18
	v_max_f32_e32 v0, v0, v18
	v_or_b32_e32 v18, 0x4b, v123
	v_and_or_b32 v18, v25, s88, v18
	v_med3_f32 v19, v20, v19, v18
	v_med3_f32 v20, v21, v20, v18
	v_med3_f32 v21, v22, v21, v18
	v_med3_f32 v22, v23, v22, v18
	v_med3_f32 v23, v24, v23, v18
	v_med3_f32 v24, v34, v24, v18
	v_med3_f32 v25, v35, v34, v18
	v_med3_f32 v34, v36, v35, v18
	v_med3_f32 v35, v37, v36, v18
	v_med3_f32 v36, v38, v37, v18
	v_med3_f32 v37, v39, v38, v18
	v_med3_f32 v38, v40, v39, v18
	v_med3_f32 v39, v41, v40, v18
	v_med3_f32 v40, v42, v41, v18
	v_med3_f32 v41, v0, v42, v18
	v_max_f32_e32 v18, v18, v18
	v_max_f32_e32 v0, v0, v18
	v_or_b32_e32 v18, 0x50, v123
	v_and_or_b32 v18, v26, s88, v18
	v_med3_f32 v19, v20, v19, v18
	v_med3_f32 v20, v21, v20, v18
	v_med3_f32 v21, v22, v21, v18
	v_med3_f32 v22, v23, v22, v18
	v_med3_f32 v23, v24, v23, v18
	v_med3_f32 v24, v25, v24, v18
	v_med3_f32 v25, v34, v25, v18
	v_med3_f32 v26, v35, v34, v18
	v_med3_f32 v34, v36, v35, v18
	v_med3_f32 v35, v37, v36, v18
	v_med3_f32 v36, v38, v37, v18
	v_med3_f32 v37, v39, v38, v18
	v_med3_f32 v38, v40, v39, v18
	v_med3_f32 v39, v41, v40, v18
	v_med3_f32 v40, v0, v41, v18
	v_max_f32_e32 v18, v18, v18
	v_max_f32_e32 v0, v0, v18
	v_or_b32_e32 v18, 0x51, v123
	v_and_or_b32 v18, v27, s88, v18
	v_med3_f32 v19, v20, v19, v18
	v_med3_f32 v20, v21, v20, v18
	v_med3_f32 v21, v22, v21, v18
	v_med3_f32 v22, v23, v22, v18
	v_med3_f32 v23, v24, v23, v18
	v_med3_f32 v24, v25, v24, v18
	v_med3_f32 v25, v26, v25, v18
	v_med3_f32 v26, v34, v26, v18
	v_med3_f32 v27, v35, v34, v18
	v_med3_f32 v34, v36, v35, v18
	v_med3_f32 v35, v37, v36, v18
	v_med3_f32 v36, v38, v37, v18
	v_med3_f32 v37, v39, v38, v18
	v_med3_f32 v38, v40, v39, v18
	v_med3_f32 v39, v0, v40, v18
	v_max_f32_e32 v18, v18, v18
	v_max_f32_e32 v0, v0, v18
	v_or_b32_e32 v18, 0x52, v123
	v_and_or_b32 v18, v28, s88, v18
	v_med3_f32 v19, v20, v19, v18
	v_med3_f32 v20, v21, v20, v18
	v_med3_f32 v21, v22, v21, v18
	v_med3_f32 v22, v23, v22, v18
	v_med3_f32 v23, v24, v23, v18
	v_med3_f32 v24, v25, v24, v18
	v_med3_f32 v25, v26, v25, v18
	v_med3_f32 v26, v27, v26, v18
	v_med3_f32 v27, v34, v27, v18
	v_med3_f32 v28, v35, v34, v18
	v_med3_f32 v34, v36, v35, v18
	v_med3_f32 v35, v37, v36, v18
	v_med3_f32 v36, v38, v37, v18
	v_med3_f32 v37, v39, v38, v18
	v_med3_f32 v38, v0, v39, v18
	v_max_f32_e32 v18, v18, v18
	v_max_f32_e32 v0, v0, v18
	v_or_b32_e32 v18, 0x53, v123
	v_and_or_b32 v18, v29, s88, v18
	v_med3_f32 v19, v20, v19, v18
	v_med3_f32 v20, v21, v20, v18
	v_med3_f32 v21, v22, v21, v18
	v_med3_f32 v22, v23, v22, v18
	v_med3_f32 v23, v24, v23, v18
	v_med3_f32 v24, v25, v24, v18
	v_med3_f32 v25, v26, v25, v18
	v_med3_f32 v26, v27, v26, v18
	v_med3_f32 v27, v28, v27, v18
	v_med3_f32 v28, v34, v28, v18
	v_med3_f32 v29, v35, v34, v18
	v_med3_f32 v34, v36, v35, v18
	v_med3_f32 v35, v37, v36, v18
	v_med3_f32 v36, v38, v37, v18
	v_med3_f32 v37, v0, v38, v18
	v_max_f32_e32 v18, v18, v18
	v_max_f32_e32 v0, v0, v18
	v_or_b32_e32 v18, 0x58, v123
	v_and_or_b32 v18, v30, s88, v18
	v_med3_f32 v19, v20, v19, v18
	v_med3_f32 v20, v21, v20, v18
	v_med3_f32 v21, v22, v21, v18
	v_med3_f32 v22, v23, v22, v18
	v_med3_f32 v23, v24, v23, v18
	v_med3_f32 v24, v25, v24, v18
	v_med3_f32 v25, v26, v25, v18
	v_med3_f32 v26, v27, v26, v18
	v_med3_f32 v27, v28, v27, v18
	v_med3_f32 v28, v29, v28, v18
	v_med3_f32 v29, v34, v29, v18
; DI void ins16n(float (&t)[16], float x, int nf) {
; #pragma unroll
;   for (int i = 15; i >= 1; --i)
;     if (i <= nf) t[i] = __builtin_amdgcn_fmed3f(t[i - 1], t[i], x);
;   t[0] = fmaxf(t[0], x);
; }
; DI void phase_peer_q(const Params& p, int layer, u16* lds, const int WAVE_S) {
;     ...
;       for (int nt = 0; nt < 4; ++nt)
; #pragma unroll
;         for (int i = 0; i < 16; ++i) {
;           const uint32_t n = nt * 32 + (i & 3) + 8 * (i >> 2) + 4 * h;
;           const float v = __uint_as_float((__float_as_uint(acc[nt][0][i]) & ~127u) | n);
;           ins16n(t, v, nt * 16 + i);
	v_med3_f32 v30, v35, v34, v18
	v_med3_f32 v34, v36, v35, v18
	v_med3_f32 v35, v37, v36, v18
	v_med3_f32 v36, v0, v37, v18
	v_max_f32_e32 v18, v18, v18
	v_max_f32_e32 v0, v0, v18
	v_or_b32_e32 v18, 0x59, v123
	v_and_or_b32 v18, v31, s88, v18
	v_med3_f32 v19, v20, v19, v18
	v_med3_f32 v20, v21, v20, v18
	v_med3_f32 v21, v22, v21, v18
	v_med3_f32 v22, v23, v22, v18
	v_med3_f32 v23, v24, v23, v18
	v_med3_f32 v24, v25, v24, v18
	v_med3_f32 v25, v26, v25, v18
	v_med3_f32 v26, v27, v26, v18
	v_med3_f32 v27, v28, v27, v18
	v_med3_f32 v28, v29, v28, v18
	v_med3_f32 v29, v30, v29, v18
	v_med3_f32 v30, v34, v30, v18
	v_med3_f32 v31, v35, v34, v18
	v_med3_f32 v34, v36, v35, v18
	v_med3_f32 v35, v0, v36, v18
	v_max_f32_e32 v18, v18, v18
	v_max_f32_e32 v0, v0, v18
	v_or_b32_e32 v18, 0x5a, v123
	v_and_or_b32 v18, v32, s88, v18
	v_med3_f32 v19, v20, v19, v18
	v_med3_f32 v20, v21, v20, v18
	v_med3_f32 v21, v22, v21, v18
	v_med3_f32 v22, v23, v22, v18
	v_med3_f32 v23, v24, v23, v18
	v_med3_f32 v24, v25, v24, v18
	v_med3_f32 v25, v26, v25, v18
	v_med3_f32 v26, v27, v26, v18
	v_med3_f32 v27, v28, v27, v18
	v_med3_f32 v28, v29, v28, v18
	v_med3_f32 v29, v30, v29, v18
	v_med3_f32 v30, v31, v30, v18
	v_med3_f32 v31, v34, v31, v18
	v_med3_f32 v32, v35, v34, v18
	v_med3_f32 v34, v0, v35, v18
	v_max_f32_e32 v18, v18, v18
	v_max_f32_e32 v0, v0, v18
	v_or_b32_e32 v18, 0x5b, v123
	v_and_or_b32 v18, v33, s88, v18
	v_med3_f32 v19, v20, v19, v18
	v_med3_f32 v20, v21, v20, v18
	v_med3_f32 v21, v22, v21, v18
	v_med3_f32 v22, v23, v22, v18
	v_med3_f32 v23, v24, v23, v18
	v_med3_f32 v24, v25, v24, v18
	v_med3_f32 v25, v26, v25, v18
	v_med3_f32 v26, v27, v26, v18
	v_med3_f32 v27, v28, v27, v18
	v_med3_f32 v28, v29, v28, v18
	v_med3_f32 v29, v30, v29, v18
	v_med3_f32 v30, v31, v30, v18
	v_med3_f32 v31, v32, v31, v18
	v_med3_f32 v32, v34, v32, v18
	v_med3_f32 v33, v0, v34, v18
	v_max_f32_e32 v18, v18, v18
	v_max_f32_e32 v0, v0, v18
	v_or_b32_e32 v18, 0x60, v123
	v_and_or_b32 v2, v2, s88, v18
	v_med3_f32 v18, v20, v19, v2
	v_med3_f32 v19, v21, v20, v2
	v_med3_f32 v20, v22, v21, v2
	v_med3_f32 v21, v23, v22, v2
	v_med3_f32 v22, v24, v23, v2
	v_med3_f32 v23, v25, v24, v2
	v_med3_f32 v24, v26, v25, v2
	v_med3_f32 v25, v27, v26, v2
	v_med3_f32 v26, v28, v27, v2
	v_med3_f32 v27, v29, v28, v2
	v_med3_f32 v28, v30, v29, v2
	v_med3_f32 v29, v31, v30, v2
	v_med3_f32 v30, v32, v31, v2
	v_med3_f32 v31, v33, v32, v2
	v_med3_f32 v32, v0, v33, v2
	v_max_f32_e32 v2, v2, v2
	v_max_f32_e32 v0, v0, v2
	v_or_b32_e32 v2, 0x61, v123
	v_and_or_b32 v2, v3, s88, v2
	v_med3_f32 v3, v19, v18, v2
	v_med3_f32 v18, v20, v19, v2
	v_med3_f32 v19, v21, v20, v2
	v_med3_f32 v20, v22, v21, v2
	v_med3_f32 v21, v23, v22, v2
	v_med3_f32 v22, v24, v23, v2
	v_med3_f32 v23, v25, v24, v2
	v_med3_f32 v24, v26, v25, v2
	v_med3_f32 v25, v27, v26, v2
	v_med3_f32 v26, v28, v27, v2
	v_med3_f32 v27, v29, v28, v2
	v_med3_f32 v28, v30, v29, v2
	v_med3_f32 v29, v31, v30, v2
	v_med3_f32 v30, v32, v31, v2
	v_med3_f32 v31, v0, v32, v2
	v_max_f32_e32 v2, v2, v2
	v_max_f32_e32 v0, v0, v2
	v_or_b32_e32 v2, 0x62, v123
	v_and_or_b32 v2, v4, s88, v2
	v_med3_f32 v3, v18, v3, v2
	v_med3_f32 v4, v19, v18, v2
	v_med3_f32 v18, v20, v19, v2
	v_med3_f32 v19, v21, v20, v2
	v_med3_f32 v20, v22, v21, v2
	v_med3_f32 v21, v23, v22, v2
	v_med3_f32 v22, v24, v23, v2
	v_med3_f32 v23, v25, v24, v2
	v_med3_f32 v24, v26, v25, v2
	v_med3_f32 v25, v27, v26, v2
	v_med3_f32 v26, v28, v27, v2
	v_med3_f32 v27, v29, v28, v2
	v_med3_f32 v28, v30, v29, v2
	v_med3_f32 v29, v31, v30, v2
	v_med3_f32 v30, v0, v31, v2
	v_max_f32_e32 v2, v2, v2
	v_max_f32_e32 v0, v0, v2
	v_or_b32_e32 v2, 0x63, v123
	v_and_or_b32 v2, v5, s88, v2
	v_med3_f32 v3, v4, v3, v2
	v_med3_f32 v4, v18, v4, v2
	v_med3_f32 v5, v19, v18, v2
	v_med3_f32 v18, v20, v19, v2
	v_med3_f32 v19, v21, v20, v2
	v_med3_f32 v20, v22, v21, v2
	v_med3_f32 v21, v23, v22, v2
	v_med3_f32 v22, v24, v23, v2
	v_med3_f32 v23, v25, v24, v2
	v_med3_f32 v24, v26, v25, v2
	v_med3_f32 v25, v27, v26, v2
	v_med3_f32 v26, v28, v27, v2
	v_med3_f32 v27, v29, v28, v2
	v_med3_f32 v28, v30, v29, v2
	v_med3_f32 v29, v0, v30, v2
	v_max_f32_e32 v2, v2, v2
	v_max_f32_e32 v0, v0, v2
	v_or_b32_e32 v2, 0x68, v123
	v_and_or_b32 v2, v6, s88, v2
	v_med3_f32 v3, v4, v3, v2
	v_med3_f32 v4, v5, v4, v2
	v_med3_f32 v5, v18, v5, v2
	v_med3_f32 v6, v19, v18, v2
	v_med3_f32 v18, v20, v19, v2
	v_med3_f32 v19, v21, v20, v2
	v_med3_f32 v20, v22, v21, v2
	v_med3_f32 v21, v23, v22, v2
	v_med3_f32 v22, v24, v23, v2
	v_med3_f32 v23, v25, v24, v2
	v_med3_f32 v24, v26, v25, v2
	v_med3_f32 v25, v27, v26, v2
	v_med3_f32 v26, v28, v27, v2
	v_med3_f32 v27, v29, v28, v2
	v_med3_f32 v28, v0, v29, v2
	v_max_f32_e32 v2, v2, v2
	v_max_f32_e32 v0, v0, v2
	v_or_b32_e32 v2, 0x69, v123
	v_and_or_b32 v2, v7, s88, v2
	v_med3_f32 v3, v4, v3, v2
	v_med3_f32 v4, v5, v4, v2
	v_med3_f32 v5, v6, v5, v2
	v_med3_f32 v6, v18, v6, v2
	v_med3_f32 v7, v19, v18, v2
	v_med3_f32 v18, v20, v19, v2
	v_med3_f32 v19, v21, v20, v2
	v_med3_f32 v20, v22, v21, v2
	v_med3_f32 v21, v23, v22, v2
	v_med3_f32 v22, v24, v23, v2
	v_med3_f32 v23, v25, v24, v2
	v_med3_f32 v24, v26, v25, v2
	v_med3_f32 v25, v27, v26, v2
	v_med3_f32 v26, v28, v27, v2
	v_med3_f32 v27, v0, v28, v2
	v_max_f32_e32 v2, v2, v2
	v_max_f32_e32 v0, v0, v2
	v_or_b32_e32 v2, 0x6a, v123
	v_and_or_b32 v2, v8, s88, v2
	v_med3_f32 v3, v4, v3, v2
	v_med3_f32 v4, v5, v4, v2
	v_med3_f32 v5, v6, v5, v2
	v_med3_f32 v6, v7, v6, v2
	v_med3_f32 v7, v18, v7, v2
	v_med3_f32 v8, v19, v18, v2
	v_med3_f32 v18, v20, v19, v2
	v_med3_f32 v19, v21, v20, v2
	v_med3_f32 v20, v22, v21, v2
	v_med3_f32 v21, v23, v22, v2
	v_med3_f32 v22, v24, v23, v2
; DI void ins16n(float (&t)[16], float x, int nf) {
; #pragma unroll
;   for (int i = 15; i >= 1; --i)
;     if (i <= nf) t[i] = __builtin_amdgcn_fmed3f(t[i - 1], t[i], x);
;   t[0] = fmaxf(t[0], x);
; }
; DI void phase_peer_q(const Params& p, int layer, u16* lds, const int WAVE_S) {
;     ...
;       for (int nt = 0; nt < 4; ++nt)
; #pragma unroll
;         for (int i = 0; i < 16; ++i) {
;           const uint32_t n = nt * 32 + (i & 3) + 8 * (i >> 2) + 4 * h;
;           const float v = __uint_as_float((__float_as_uint(acc[nt][0][i]) & ~127u) | n);
;           ins16n(t, v, nt * 16 + i);
;         }
;       float o16[16];
; #pragma unroll
;       for (int i = 0; i < 16; ++i) {
;         auto rr = __builtin_amdgcn_permlane32_swap(__float_as_uint(t[i]), __float_as_uint(t[i]), false, false);
;         o16[i] = __uint_as_float(h ? rr[0] : rr[1]);
;       }
	v_med3_f32 v23, v25, v24, v2
	v_med3_f32 v24, v26, v25, v2
	v_med3_f32 v25, v27, v26, v2
	v_med3_f32 v26, v0, v27, v2
	v_max_f32_e32 v2, v2, v2
	v_max_f32_e32 v0, v0, v2
	v_or_b32_e32 v2, 0x6b, v123
	v_and_or_b32 v2, v9, s88, v2
	v_med3_f32 v3, v4, v3, v2
	v_med3_f32 v4, v5, v4, v2
	v_med3_f32 v5, v6, v5, v2
	v_med3_f32 v6, v7, v6, v2
	v_med3_f32 v7, v8, v7, v2
	v_med3_f32 v8, v18, v8, v2
	v_med3_f32 v9, v19, v18, v2
	v_med3_f32 v18, v20, v19, v2
	v_med3_f32 v19, v21, v20, v2
	v_med3_f32 v20, v22, v21, v2
	v_med3_f32 v21, v23, v22, v2
	v_med3_f32 v22, v24, v23, v2
	v_med3_f32 v23, v25, v24, v2
	v_med3_f32 v24, v26, v25, v2
	v_med3_f32 v25, v0, v26, v2
	v_max_f32_e32 v2, v2, v2
	v_max_f32_e32 v0, v0, v2
	v_and_or_b32 v2, v10, s88, v125
	v_med3_f32 v3, v4, v3, v2
	v_med3_f32 v4, v5, v4, v2
	v_med3_f32 v5, v6, v5, v2
	v_med3_f32 v6, v7, v6, v2
	v_med3_f32 v7, v8, v7, v2
	v_med3_f32 v8, v9, v8, v2
	v_med3_f32 v9, v18, v9, v2
	v_med3_f32 v10, v19, v18, v2
	v_med3_f32 v18, v20, v19, v2
	v_med3_f32 v19, v21, v20, v2
	v_med3_f32 v20, v22, v21, v2
	v_med3_f32 v21, v23, v22, v2
	v_med3_f32 v22, v24, v23, v2
	v_med3_f32 v23, v25, v24, v2
	v_med3_f32 v24, v0, v25, v2
	v_max_f32_e32 v2, v2, v2
	v_max_f32_e32 v0, v0, v2
	v_and_or_b32 v2, v11, s88, v126
	v_med3_f32 v3, v4, v3, v2
	v_med3_f32 v4, v5, v4, v2
	v_med3_f32 v5, v6, v5, v2
	v_med3_f32 v6, v7, v6, v2
	v_med3_f32 v7, v8, v7, v2
	v_med3_f32 v8, v9, v8, v2
	v_med3_f32 v9, v10, v9, v2
	v_med3_f32 v10, v18, v10, v2
	v_med3_f32 v11, v19, v18, v2
	v_med3_f32 v18, v20, v19, v2
	v_med3_f32 v19, v21, v20, v2
	v_med3_f32 v20, v22, v21, v2
	v_med3_f32 v21, v23, v22, v2
	v_med3_f32 v22, v24, v23, v2
	v_med3_f32 v23, v0, v24, v2
	v_max_f32_e32 v2, v2, v2
	v_max_f32_e32 v0, v0, v2
	v_and_or_b32 v2, v12, s88, v127
	v_med3_f32 v3, v4, v3, v2
	v_med3_f32 v4, v5, v4, v2
	v_med3_f32 v5, v6, v5, v2
	v_med3_f32 v6, v7, v6, v2
	v_med3_f32 v7, v8, v7, v2
	v_med3_f32 v8, v9, v8, v2
	v_med3_f32 v9, v10, v9, v2
	v_med3_f32 v10, v11, v10, v2
	v_med3_f32 v11, v18, v11, v2
	v_med3_f32 v12, v19, v18, v2
	v_med3_f32 v18, v20, v19, v2
	v_med3_f32 v19, v21, v20, v2
	v_med3_f32 v20, v22, v21, v2
	v_med3_f32 v21, v23, v22, v2
	v_med3_f32 v22, v0, v23, v2
	v_max_f32_e32 v2, v2, v2
	v_max_f32_e32 v0, v0, v2
	v_and_or_b32 v2, v13, s88, v128
	v_med3_f32 v3, v4, v3, v2
	v_med3_f32 v4, v5, v4, v2
	v_med3_f32 v5, v6, v5, v2
	v_med3_f32 v6, v7, v6, v2
	v_med3_f32 v7, v8, v7, v2
	v_med3_f32 v8, v9, v8, v2
	v_med3_f32 v9, v10, v9, v2
	v_med3_f32 v10, v11, v10, v2
	v_med3_f32 v11, v12, v11, v2
	v_med3_f32 v12, v18, v12, v2
	v_med3_f32 v13, v19, v18, v2
	v_med3_f32 v18, v20, v19, v2
	v_med3_f32 v19, v21, v20, v2
	v_med3_f32 v20, v22, v21, v2
	v_med3_f32 v21, v0, v22, v2
	v_max_f32_e32 v2, v2, v2
	v_max_f32_e32 v0, v0, v2
	v_and_or_b32 v2, v14, s88, v129
	v_med3_f32 v3, v4, v3, v2
	v_med3_f32 v4, v5, v4, v2
	v_med3_f32 v5, v6, v5, v2
	v_med3_f32 v6, v7, v6, v2
	v_med3_f32 v7, v8, v7, v2
	v_med3_f32 v8, v9, v8, v2
	v_med3_f32 v9, v10, v9, v2
	v_med3_f32 v10, v11, v10, v2
	v_med3_f32 v11, v12, v11, v2
	v_med3_f32 v12, v13, v12, v2
	v_med3_f32 v13, v18, v13, v2
	v_med3_f32 v14, v19, v18, v2
	v_med3_f32 v18, v20, v19, v2
	v_med3_f32 v19, v21, v20, v2
	v_med3_f32 v20, v0, v21, v2
	v_max_f32_e32 v2, v2, v2
	v_max_f32_e32 v0, v0, v2
	v_and_or_b32 v2, v15, s88, v130
	v_med3_f32 v3, v4, v3, v2
	v_med3_f32 v4, v5, v4, v2
	v_med3_f32 v5, v6, v5, v2
	v_med3_f32 v6, v7, v6, v2
	v_med3_f32 v7, v8, v7, v2
	v_med3_f32 v8, v9, v8, v2
	v_med3_f32 v9, v10, v9, v2
	v_med3_f32 v10, v11, v10, v2
	v_med3_f32 v11, v12, v11, v2
	v_med3_f32 v12, v13, v12, v2
	v_med3_f32 v13, v14, v13, v2
	v_med3_f32 v14, v18, v14, v2
	v_med3_f32 v15, v19, v18, v2
	v_med3_f32 v18, v20, v19, v2
	v_med3_f32 v19, v0, v20, v2
	v_max_f32_e32 v2, v2, v2
	v_max_f32_e32 v0, v0, v2
	v_and_or_b32 v2, v16, s88, v131
	v_med3_f32 v3, v4, v3, v2
	v_med3_f32 v4, v5, v4, v2
	v_med3_f32 v5, v6, v5, v2
	v_med3_f32 v6, v7, v6, v2
	v_med3_f32 v7, v8, v7, v2
	v_med3_f32 v8, v9, v8, v2
	v_med3_f32 v9, v10, v9, v2
	v_med3_f32 v10, v11, v10, v2
	v_med3_f32 v11, v12, v11, v2
	v_med3_f32 v12, v13, v12, v2
	v_med3_f32 v13, v14, v13, v2
	v_med3_f32 v14, v15, v14, v2
	v_med3_f32 v15, v18, v15, v2
	v_med3_f32 v16, v19, v18, v2
	v_med3_f32 v18, v0, v19, v2
	v_max_f32_e32 v2, v2, v2
	v_max_f32_e32 v0, v0, v2
	v_and_or_b32 v2, v17, s88, v132
	v_med3_f32 v3, v4, v3, v2
	v_med3_f32 v4, v5, v4, v2
	v_med3_f32 v5, v6, v5, v2
	v_med3_f32 v6, v7, v6, v2
	v_med3_f32 v7, v8, v7, v2
	v_med3_f32 v8, v9, v8, v2
	v_med3_f32 v9, v10, v9, v2
	v_med3_f32 v10, v11, v10, v2
	v_med3_f32 v11, v12, v11, v2
	v_med3_f32 v12, v13, v12, v2
	v_med3_f32 v13, v14, v13, v2
	v_med3_f32 v14, v15, v14, v2
	v_med3_f32 v15, v16, v15, v2
	v_med3_f32 v16, v18, v16, v2
	v_med3_f32 v17, v0, v18, v2
	v_max_f32_e32 v2, v2, v2
	v_max_f32_e32 v0, v0, v2
	v_mov_b32_e32 v2, v0
	v_mov_b32_e32 v18, v0
	s_nop 1
	v_permlane32_swap_b32_e32 v2, v18
	v_cndmask_b32_e64 v2, v2, v18, s[34:35]
	v_mov_b32_e32 v18, v17
	v_mov_b32_e32 v19, v17
	s_nop 1
	v_permlane32_swap_b32_e32 v18, v19
	v_cndmask_b32_e64 v18, v18, v19, s[34:35]
	v_mov_b32_e32 v19, v16
	v_mov_b32_e32 v20, v16
	s_nop 1
	v_permlane32_swap_b32_e32 v19, v20
	v_cndmask_b32_e64 v19, v19, v20, s[34:35]
	v_mov_b32_e32 v20, v15
	v_mov_b32_e32 v21, v15
	s_nop 1
	v_permlane32_swap_b32_e32 v20, v21
	v_cndmask_b32_e64 v20, v20, v21, s[34:35]
	v_mov_b32_e32 v21, v14
	v_mov_b32_e32 v22, v14
	s_nop 1
	v_permlane32_swap_b32_e32 v21, v22
	v_cndmask_b32_e64 v21, v21, v22, s[34:35]
	v_mov_b32_e32 v22, v13
	v_mov_b32_e32 v23, v13
	s_nop 1
	v_permlane32_swap_b32_e32 v22, v23
	v_cndmask_b32_e64 v22, v22, v23, s[34:35]
; DI void ins16(float (&t)[16], float x) {
; #pragma unroll
;   for (int i = 15; i >= 1; --i) t[i] = __builtin_amdgcn_fmed3f(t[i - 1], t[i], x);
;   t[0] = fmaxf(t[0], x);
; }
; DI void phase_peer_q(const Params& p, int layer, u16* lds, const int WAVE_S) {
;     ...
; #pragma unroll
;       for (int i = 0; i < 16; ++i) {
;         auto rr = __builtin_amdgcn_permlane32_swap(__float_as_uint(t[i]), __float_as_uint(t[i]), false, false);
;         o16[i] = __uint_as_float(h ? rr[0] : rr[1]);
;       }
; #pragma unroll
;       for (int i = 0; i < 16; ++i) ins16(t, o16[i]);
	v_mov_b32_e32 v23, v12
	v_mov_b32_e32 v24, v12
	s_nop 1
	v_permlane32_swap_b32_e32 v23, v24
	v_cndmask_b32_e64 v23, v23, v24, s[34:35]
	v_mov_b32_e32 v24, v11
	v_mov_b32_e32 v25, v11
	s_nop 1
	v_permlane32_swap_b32_e32 v24, v25
	v_cndmask_b32_e64 v24, v24, v25, s[34:35]
	v_mov_b32_e32 v25, v10
	v_mov_b32_e32 v26, v10
	s_nop 1
	v_permlane32_swap_b32_e32 v25, v26
	v_cndmask_b32_e64 v25, v25, v26, s[34:35]
	v_mov_b32_e32 v26, v9
	v_mov_b32_e32 v27, v9
	s_nop 1
	v_permlane32_swap_b32_e32 v26, v27
	v_cndmask_b32_e64 v26, v26, v27, s[34:35]
	v_mov_b32_e32 v27, v8
	v_mov_b32_e32 v28, v8
	s_nop 1
	v_permlane32_swap_b32_e32 v27, v28
	v_cndmask_b32_e64 v27, v27, v28, s[34:35]
	v_mov_b32_e32 v28, v7
	v_mov_b32_e32 v29, v7
	s_nop 1
	v_permlane32_swap_b32_e32 v28, v29
	v_cndmask_b32_e64 v28, v28, v29, s[34:35]
	v_mov_b32_e32 v29, v6
	v_mov_b32_e32 v30, v6
	s_nop 1
	v_permlane32_swap_b32_e32 v29, v30
	v_cndmask_b32_e64 v29, v29, v30, s[34:35]
	v_mov_b32_e32 v30, v5
	v_mov_b32_e32 v31, v5
	s_nop 1
	v_permlane32_swap_b32_e32 v30, v31
	v_cndmask_b32_e64 v30, v30, v31, s[34:35]
	v_mov_b32_e32 v31, v4
	v_mov_b32_e32 v32, v4
	s_nop 1
	v_permlane32_swap_b32_e32 v31, v32
	v_cndmask_b32_e64 v31, v31, v32, s[34:35]
	v_mov_b32_e32 v32, v3
	v_mov_b32_e32 v33, v3
	v_med3_f32 v3, v4, v3, v2
	v_med3_f32 v4, v5, v4, v2
	v_med3_f32 v5, v6, v5, v2
	v_med3_f32 v6, v7, v6, v2
	v_med3_f32 v7, v8, v7, v2
	v_med3_f32 v8, v9, v8, v2
	v_med3_f32 v9, v10, v9, v2
	v_med3_f32 v10, v11, v10, v2
	v_med3_f32 v11, v12, v11, v2
	v_med3_f32 v12, v13, v12, v2
	v_med3_f32 v13, v14, v13, v2
	v_med3_f32 v14, v15, v14, v2
	v_med3_f32 v15, v16, v15, v2
	v_med3_f32 v16, v17, v16, v2
	v_med3_f32 v17, v0, v17, v2
	v_max_f32_e32 v2, v2, v2
	v_max_f32_e32 v0, v0, v2
	v_med3_f32 v2, v4, v3, v18
	v_med3_f32 v3, v5, v4, v18
	v_med3_f32 v4, v6, v5, v18
	v_med3_f32 v5, v7, v6, v18
	v_med3_f32 v6, v8, v7, v18
	v_med3_f32 v7, v9, v8, v18
	v_med3_f32 v8, v10, v9, v18
	v_med3_f32 v9, v11, v10, v18
	v_med3_f32 v10, v12, v11, v18
	v_med3_f32 v11, v13, v12, v18
	v_med3_f32 v12, v14, v13, v18
	v_med3_f32 v13, v15, v14, v18
	v_med3_f32 v14, v16, v15, v18
	v_med3_f32 v15, v17, v16, v18
	v_med3_f32 v16, v0, v17, v18
	v_max_f32_e32 v17, v18, v18
	v_max_f32_e32 v0, v0, v17
	v_max_f32_e32 v17, v19, v19
	v_med3_f32 v2, v3, v2, v19
	v_med3_f32 v3, v4, v3, v19
	v_med3_f32 v4, v5, v4, v19
	v_med3_f32 v5, v6, v5, v19
	v_med3_f32 v6, v7, v6, v19
	v_med3_f32 v7, v8, v7, v19
	v_med3_f32 v8, v9, v8, v19
	v_med3_f32 v9, v10, v9, v19
	v_med3_f32 v10, v11, v10, v19
	v_med3_f32 v11, v12, v11, v19
	v_med3_f32 v12, v13, v12, v19
	v_med3_f32 v13, v14, v13, v19
	v_med3_f32 v14, v15, v14, v19
	v_med3_f32 v15, v16, v15, v19
	v_med3_f32 v16, v0, v16, v19
	v_max_f32_e32 v0, v0, v17
	v_max_f32_e32 v17, v20, v20
	v_med3_f32 v2, v3, v2, v20
	v_med3_f32 v3, v4, v3, v20
	v_med3_f32 v4, v5, v4, v20
	v_med3_f32 v5, v6, v5, v20
	v_med3_f32 v6, v7, v6, v20
	v_med3_f32 v7, v8, v7, v20
	v_med3_f32 v8, v9, v8, v20
	v_med3_f32 v9, v10, v9, v20
	v_med3_f32 v10, v11, v10, v20
	v_med3_f32 v11, v12, v11, v20
	v_med3_f32 v12, v13, v12, v20
	v_med3_f32 v13, v14, v13, v20
	v_med3_f32 v14, v15, v14, v20
	v_med3_f32 v15, v16, v15, v20
	v_med3_f32 v16, v0, v16, v20
	v_max_f32_e32 v0, v0, v17
	v_max_f32_e32 v17, v21, v21
	v_med3_f32 v2, v3, v2, v21
	v_med3_f32 v3, v4, v3, v21
	v_med3_f32 v4, v5, v4, v21
	v_med3_f32 v5, v6, v5, v21
	v_med3_f32 v6, v7, v6, v21
	v_med3_f32 v7, v8, v7, v21
	v_med3_f32 v8, v9, v8, v21
	v_med3_f32 v9, v10, v9, v21
	v_med3_f32 v10, v11, v10, v21
	v_med3_f32 v11, v12, v11, v21
	v_med3_f32 v12, v13, v12, v21
	v_med3_f32 v13, v14, v13, v21
	v_med3_f32 v14, v15, v14, v21
	v_med3_f32 v15, v16, v15, v21
	v_med3_f32 v16, v0, v16, v21
	v_max_f32_e32 v0, v0, v17
	v_max_f32_e32 v17, v22, v22
	v_med3_f32 v2, v3, v2, v22
	v_med3_f32 v3, v4, v3, v22
	v_med3_f32 v4, v5, v4, v22
	v_med3_f32 v5, v6, v5, v22
	v_med3_f32 v6, v7, v6, v22
	v_med3_f32 v7, v8, v7, v22
	v_med3_f32 v8, v9, v8, v22
	v_med3_f32 v9, v10, v9, v22
	v_med3_f32 v10, v11, v10, v22
	v_med3_f32 v11, v12, v11, v22
	v_med3_f32 v12, v13, v12, v22
	v_med3_f32 v13, v14, v13, v22
	v_med3_f32 v14, v15, v14, v22
	v_med3_f32 v15, v16, v15, v22
	v_med3_f32 v16, v0, v16, v22
	v_max_f32_e32 v0, v0, v17
	v_max_f32_e32 v17, v23, v23
	v_med3_f32 v2, v3, v2, v23
	v_med3_f32 v3, v4, v3, v23
	v_med3_f32 v4, v5, v4, v23
	v_med3_f32 v5, v6, v5, v23
	v_med3_f32 v6, v7, v6, v23
	v_med3_f32 v7, v8, v7, v23
	v_med3_f32 v8, v9, v8, v23
	v_med3_f32 v9, v10, v9, v23
	v_med3_f32 v10, v11, v10, v23
	v_med3_f32 v11, v12, v11, v23
	v_med3_f32 v12, v13, v12, v23
	v_med3_f32 v13, v14, v13, v23
	v_med3_f32 v14, v15, v14, v23
	v_med3_f32 v15, v16, v15, v23
	v_med3_f32 v16, v0, v16, v23
	v_max_f32_e32 v0, v0, v17
	v_max_f32_e32 v17, v24, v24
	v_med3_f32 v2, v3, v2, v24
	v_med3_f32 v3, v4, v3, v24
; DI void ins16(float (&t)[16], float x) {
; #pragma unroll
;   for (int i = 15; i >= 1; --i) t[i] = __builtin_amdgcn_fmed3f(t[i - 1], t[i], x);
;   t[0] = fmaxf(t[0], x);
; }
; DI void phase_peer_q(const Params& p, int layer, u16* lds, const int WAVE_S) {
;     ...
; #pragma unroll
;       for (int i = 0; i < 16; ++i) ins16(t, o16[i]);
;       if (half == 0) {
; #pragma unroll
;         for (int i = 0; i < 16; ++i) t0[i] = t[i];
	v_med3_f32 v4, v5, v4, v24
	v_med3_f32 v5, v6, v5, v24
	v_med3_f32 v6, v7, v6, v24
	v_med3_f32 v7, v8, v7, v24
	v_med3_f32 v8, v9, v8, v24
	v_med3_f32 v9, v10, v9, v24
	v_med3_f32 v10, v11, v10, v24
	v_med3_f32 v11, v12, v11, v24
	v_med3_f32 v12, v13, v12, v24
	v_med3_f32 v13, v14, v13, v24
	v_med3_f32 v14, v15, v14, v24
	v_med3_f32 v15, v16, v15, v24
	v_med3_f32 v16, v0, v16, v24
	v_max_f32_e32 v0, v0, v17
	v_med3_f32 v2, v3, v2, v25
	v_med3_f32 v3, v4, v3, v25
	v_med3_f32 v4, v5, v4, v25
	v_med3_f32 v5, v6, v5, v25
	v_med3_f32 v6, v7, v6, v25
	v_med3_f32 v7, v8, v7, v25
	v_med3_f32 v8, v9, v8, v25
	v_med3_f32 v9, v10, v9, v25
	v_med3_f32 v10, v11, v10, v25
	v_med3_f32 v11, v12, v11, v25
	v_med3_f32 v12, v13, v12, v25
	v_med3_f32 v13, v14, v13, v25
	v_med3_f32 v14, v15, v14, v25
	v_med3_f32 v15, v16, v15, v25
	v_med3_f32 v16, v0, v16, v25
	v_max_f32_e32 v17, v25, v25
	v_max_f32_e32 v0, v0, v17
	v_med3_f32 v2, v3, v2, v26
	v_med3_f32 v3, v4, v3, v26
	v_med3_f32 v4, v5, v4, v26
	v_med3_f32 v5, v6, v5, v26
	v_med3_f32 v6, v7, v6, v26
	v_med3_f32 v7, v8, v7, v26
	v_med3_f32 v8, v9, v8, v26
	v_med3_f32 v9, v10, v9, v26
	v_med3_f32 v10, v11, v10, v26
	v_med3_f32 v11, v12, v11, v26
	v_med3_f32 v12, v13, v12, v26
	v_med3_f32 v13, v14, v13, v26
	v_med3_f32 v14, v15, v14, v26
	v_med3_f32 v15, v16, v15, v26
	v_max_f32_e32 v17, v26, v26
	v_med3_f32 v16, v0, v16, v26
	v_max_f32_e32 v0, v0, v17
	v_med3_f32 v2, v3, v2, v27
	v_med3_f32 v3, v4, v3, v27
	v_med3_f32 v4, v5, v4, v27
	v_med3_f32 v5, v6, v5, v27
	v_med3_f32 v6, v7, v6, v27
	v_med3_f32 v7, v8, v7, v27
	v_med3_f32 v8, v9, v8, v27
	v_med3_f32 v9, v10, v9, v27
	v_med3_f32 v10, v11, v10, v27
	v_med3_f32 v11, v12, v11, v27
	v_med3_f32 v12, v13, v12, v27
	v_med3_f32 v13, v14, v13, v27
	v_med3_f32 v14, v15, v14, v27
	v_max_f32_e32 v17, v27, v27
	v_med3_f32 v15, v16, v15, v27
	v_med3_f32 v16, v0, v16, v27
	v_max_f32_e32 v0, v0, v17
	v_med3_f32 v2, v3, v2, v28
	v_med3_f32 v3, v4, v3, v28
	v_med3_f32 v4, v5, v4, v28
	v_med3_f32 v5, v6, v5, v28
	v_med3_f32 v6, v7, v6, v28
	v_med3_f32 v7, v8, v7, v28
	v_med3_f32 v8, v9, v8, v28
	v_med3_f32 v9, v10, v9, v28
	v_med3_f32 v10, v11, v10, v28
	v_med3_f32 v11, v12, v11, v28
	v_med3_f32 v12, v13, v12, v28
	v_med3_f32 v13, v14, v13, v28
	v_max_f32_e32 v17, v28, v28
	v_med3_f32 v14, v15, v14, v28
	v_med3_f32 v15, v16, v15, v28
	v_med3_f32 v16, v0, v16, v28
	v_max_f32_e32 v0, v0, v17
	v_med3_f32 v2, v3, v2, v29
	v_med3_f32 v3, v4, v3, v29
	v_med3_f32 v4, v5, v4, v29
	v_med3_f32 v5, v6, v5, v29
	v_med3_f32 v6, v7, v6, v29
	v_med3_f32 v7, v8, v7, v29
	v_med3_f32 v8, v9, v8, v29
	v_med3_f32 v9, v10, v9, v29
	v_med3_f32 v10, v11, v10, v29
	v_med3_f32 v11, v12, v11, v29
	v_med3_f32 v12, v13, v12, v29
	v_max_f32_e32 v17, v29, v29
	v_permlane32_swap_b32_e32 v32, v33
	v_med3_f32 v13, v14, v13, v29
	v_med3_f32 v14, v15, v14, v29
	v_med3_f32 v15, v16, v15, v29
	v_med3_f32 v16, v0, v16, v29
	v_max_f32_e32 v0, v0, v17
	v_med3_f32 v2, v3, v2, v30
	v_med3_f32 v3, v4, v3, v30
	v_med3_f32 v4, v5, v4, v30
	v_med3_f32 v5, v6, v5, v30
	v_med3_f32 v6, v7, v6, v30
	v_med3_f32 v7, v8, v7, v30
	v_med3_f32 v8, v9, v8, v30
	v_med3_f32 v9, v10, v9, v30
	v_med3_f32 v10, v11, v10, v30
	v_med3_f32 v11, v12, v11, v30
	v_max_f32_e32 v17, v30, v30
	v_cndmask_b32_e64 v32, v32, v33, s[34:35]
	v_med3_f32 v12, v13, v12, v30
	v_med3_f32 v13, v14, v13, v30
	v_med3_f32 v14, v15, v14, v30
	v_med3_f32 v15, v16, v15, v30
	v_med3_f32 v16, v0, v16, v30
	v_max_f32_e32 v0, v0, v17
	v_med3_f32 v2, v3, v2, v31
	v_med3_f32 v3, v4, v3, v31
	v_med3_f32 v4, v5, v4, v31
	v_med3_f32 v5, v6, v5, v31
	v_med3_f32 v6, v7, v6, v31
	v_med3_f32 v7, v8, v7, v31
	v_med3_f32 v8, v9, v8, v31
	v_med3_f32 v9, v10, v9, v31
	v_med3_f32 v18, v11, v10, v31
	v_max_f32_e32 v10, v31, v31
	v_med3_f32 v19, v12, v11, v31
	v_med3_f32 v20, v13, v12, v31
	v_med3_f32 v21, v14, v13, v31
	v_med3_f32 v22, v15, v14, v31
	v_med3_f32 v23, v16, v15, v31
	v_med3_f32 v24, v0, v16, v31
	v_max_f32_e32 v0, v0, v10
	v_med3_f32 v11, v3, v2, v32
	v_max_f32_e32 v2, v32, v32
	v_med3_f32 v10, v4, v3, v32
	v_med3_f32 v13, v5, v4, v32
	v_med3_f32 v12, v6, v5, v32
	v_med3_f32 v15, v7, v6, v32
	v_med3_f32 v14, v8, v7, v32
	v_med3_f32 v17, v9, v8, v32
	v_med3_f32 v16, v18, v9, v32
	v_med3_f32 v9, v19, v18, v32
	v_med3_f32 v8, v20, v19, v32
	v_med3_f32 v7, v21, v20, v32
	v_med3_f32 v6, v22, v21, v32
	v_med3_f32 v5, v23, v22, v32
	v_med3_f32 v4, v24, v23, v32
	v_med3_f32 v3, v0, v24, v32
	v_max_f32_e32 v2, v0, v2
	s_cbranch_vccz .LBB0_388
	v_mov_b64_e32 v[18:19], v[98:99]
	v_mov_b64_e32 v[20:21], v[100:101]
	v_mov_b64_e32 v[22:23], v[102:103]
	v_mov_b64_e32 v[24:25], v[104:105]
	v_mov_b64_e32 v[26:27], v[106:107]
	v_mov_b64_e32 v[28:29], v[108:109]
	v_mov_b64_e32 v[30:31], v[110:111]
	v_mov_b64_e32 v[32:33], v[112:113]
	s_branch .LBB0_389
